# Block loops: per-mode precomputed block list (vector-built, read with v_readlane), constant DMA count per iteration, deferred PV, pair path, row sums as in-place tree after packing; compressed branch
# speedup vs baseline: 1.0523x; 1.0068x over previous
; #define LAS __attribute__((address_space(3)))
; __device__ __forceinline__ float ex2(float x) { return __builtin_amdgcn_exp2f(x); }
; __device__ __forceinline__ void cmp_sm1(const f32x4 (&sc)[4], int gr, int t0, const LAS float* bt, float (&ls)[4], int r16) {
; #pragma unroll
;     for (int cc = 0; cc < 4; ++cc) {
;         const int cend = (gr * 64 + cc * 16 + r16) * 16 + 31;
; #pragma unroll
;         for (int i = 0; i < 4; ++i) { const int dist = t0 + i - cend; ls[i] += dist >= 0 ? ex2(sc[cc][i] + bt[clampd(dist)]) : 0.f; }
;     }
; }
; __device__ __forceinline__ void nsa_quad_pre(int bg, int quad, const bf16_t* Q, const bf16_t* KV, const bf16_t* KCMP, const bf16_t* VCMPT, const float* GN, bf16_t* ONSA, ...
;     ...
;     if (ngr > 0) {
;         float ls[4] = {0.f, 0.f, 0.f, 0.f};
;         load_k(KF, KP_C(0));
;         for (int gr = 0; gr < ngr; ++gr) {
;             qk_scores(KF, qf, sc);
;             load_k(KF, KP_C(gr + 1 < ngr ? gr + 1 : 0));
;             cmp_sm1(sc, gr, t0, bt, ls, r16);
;         }
.Lcmp_top_q0p1:
	s_nop 1
	s_cmp_lt_i32 s57, s52
	s_cbranch_scc0 .Lcmp_gen_q0p1
	s_waitcnt vmcnt(0)
	v_mov_b32_e32 v228, v225
	v_mov_b32_e32 v229, v225
	v_mov_b32_e32 v230, v225
	v_mov_b32_e32 v231, v225
	s_nop 1
	v_mfma_f32_16x16x32_bf16 v[18:21], v[50:53], v[34:37], v[228:231]
	v_mfma_f32_16x16x32_bf16 v[18:21], v[54:57], v[38:41], v[18:21]
	v_mfma_f32_16x16x32_bf16 v[22:25], v[58:61], v[34:37], v[228:231]
	v_mfma_f32_16x16x32_bf16 v[22:25], v[62:65], v[38:41], v[22:25]
	v_mfma_f32_16x16x32_bf16 v[26:29], v[66:69], v[34:37], v[228:231]
	v_mfma_f32_16x16x32_bf16 v[26:29], v[70:73], v[38:41], v[26:29]
	v_mfma_f32_16x16x32_bf16 v[30:33], v[74:77], v[34:37], v[228:231]
	v_mfma_f32_16x16x32_bf16 v[30:33], v[78:81], v[38:41], v[30:33]
	s_add_i32 s1, s57, 1
	s_cmp_lt_i32 s1, s53
	s_cselect_b32 s1, s1, 0
	s_lshl_b32 s0, s1, 13
	s_add_u32 s70, s66, s0
	s_addc_u32 s71, s67, 0
	global_load_dwordx4 v[50:53], v174, s[70:71] offset:0
	global_load_dwordx4 v[54:57], v174, s[70:71] offset:64
	global_load_dwordx4 v[58:61], v174, s[70:71] offset:512
	global_load_dwordx4 v[62:65], v174, s[70:71] offset:576
	global_load_dwordx4 v[66:69], v175, s[70:71] offset:0
	global_load_dwordx4 v[70:73], v175, s[70:71] offset:64
	global_load_dwordx4 v[74:77], v175, s[70:71] offset:512
	global_load_dwordx4 v[78:81], v175, s[70:71] offset:576
	v_exp_f32_e32 v18, v18
	v_exp_f32_e32 v19, v19
	v_exp_f32_e32 v20, v20
	v_exp_f32_e32 v21, v21
	v_exp_f32_e32 v22, v22
	v_exp_f32_e32 v23, v23
	v_exp_f32_e32 v24, v24
	v_exp_f32_e32 v25, v25
	v_exp_f32_e32 v26, v26
	v_exp_f32_e32 v27, v27
	v_exp_f32_e32 v28, v28
	v_exp_f32_e32 v29, v29
	v_exp_f32_e32 v30, v30
	v_exp_f32_e32 v31, v31
	v_exp_f32_e32 v32, v32
	v_exp_f32_e32 v33, v33
	v_add_f32_e32 v18, v18, v19
	v_add_f32_e32 v20, v20, v21
	v_add_f32_e32 v22, v22, v23
	v_add_f32_e32 v24, v24, v25
	v_add_f32_e32 v26, v26, v27
	v_add_f32_e32 v28, v28, v29
	v_add_f32_e32 v30, v30, v31
	v_add_f32_e32 v32, v32, v33
	v_add_f32_e32 v18, v18, v20
	v_add_f32_e32 v22, v22, v24
	v_add_f32_e32 v26, v26, v28
	v_add_f32_e32 v30, v30, v32
	v_add_f32_e32 v18, v18, v22
	v_add_f32_e32 v26, v26, v30
	v_add_f32_e32 v18, v18, v26
	v_add_f32_e32 v170, v170, v18
	s_branch .Lcmp_nx_q0p1
; #define LAS __attribute__((address_space(3)))
; __device__ __forceinline__ float ex2(float x) { return __builtin_amdgcn_exp2f(x); }
; __device__ __forceinline__ void cmp_sm1(const f32x4 (&sc)[4], int gr, int t0, const LAS float* bt, float (&ls)[4], int r16) {
; #pragma unroll
;     for (int cc = 0; cc < 4; ++cc) {
;         const int cend = (gr * 64 + cc * 16 + r16) * 16 + 31;
; #pragma unroll
;         for (int i = 0; i < 4; ++i) { const int dist = t0 + i - cend; ls[i] += dist >= 0 ? ex2(sc[cc][i] + bt[clampd(dist)]) : 0.f; }
;     }
; }
; __device__ __forceinline__ void nsa_quad_pre(int bg, int quad, const bf16_t* Q, const bf16_t* KV, const bf16_t* KCMP, const bf16_t* VCMPT, const float* GN, bf16_t* ONSA, ...
;     ...
;     if (ngr > 0) {
;         float ls[4] = {0.f, 0.f, 0.f, 0.f};
;         load_k(KF, KP_C(0));
;         for (int gr = 0; gr < ngr; ++gr) {
;             qk_scores(KF, qf, sc);
;             load_k(KF, KP_C(gr + 1 < ngr ? gr + 1 : 0));
;             cmp_sm1(sc, gr, t0, bt, ls, r16);
;         }
.Lcmp_gen_q0p1:
	s_nop 1
	s_waitcnt vmcnt(0)
	v_mfma_f32_16x16x32_bf16 v[18:21], v[50:53], v[34:37], 0
	v_mfma_f32_16x16x32_bf16 v[18:21], v[54:57], v[38:41], v[18:21]
	v_mfma_f32_16x16x32_bf16 v[22:25], v[58:61], v[34:37], 0
	v_mfma_f32_16x16x32_bf16 v[22:25], v[62:65], v[38:41], v[22:25]
	v_mfma_f32_16x16x32_bf16 v[26:29], v[66:69], v[34:37], 0
	v_mfma_f32_16x16x32_bf16 v[26:29], v[70:73], v[38:41], v[26:29]
	v_mfma_f32_16x16x32_bf16 v[30:33], v[74:77], v[34:37], 0
	v_mfma_f32_16x16x32_bf16 v[30:33], v[78:81], v[38:41], v[30:33]
	s_add_i32 s1, s57, 1
	s_cmp_lt_i32 s1, s53
	s_cselect_b32 s1, s1, 0
	s_lshl_b32 s0, s1, 13
	s_add_u32 s70, s66, s0
	s_addc_u32 s71, s67, 0
	global_load_dwordx4 v[50:53], v174, s[70:71] offset:0
	global_load_dwordx4 v[54:57], v174, s[70:71] offset:64
	global_load_dwordx4 v[58:61], v174, s[70:71] offset:512
	global_load_dwordx4 v[62:65], v174, s[70:71] offset:576
	global_load_dwordx4 v[66:69], v175, s[70:71] offset:0
	global_load_dwordx4 v[70:73], v175, s[70:71] offset:64
	global_load_dwordx4 v[74:77], v175, s[70:71] offset:512
	global_load_dwordx4 v[78:81], v175, s[70:71] offset:576
	s_lshl_b32 s0, s57, 10
	v_subrev_u32_e32 v224, s0, v99
	v_add_u32_e32 v232, 0x0, v224
	v_min_u32_e32 v232, 0x400, v232
	v_lshl_add_u32 v232, v232, 2, v173
	ds_read_b32 v216, v232
	v_add_u32_e32 v232, 0xfffffff0, v224
	v_min_u32_e32 v232, 0x400, v232
	v_lshl_add_u32 v232, v232, 2, v173
	ds_read_b32 v217, v232
	v_add_u32_e32 v232, 0xffffffe0, v224
	v_min_u32_e32 v232, 0x400, v232
	v_lshl_add_u32 v232, v232, 2, v173
	ds_read_b32 v218, v232
	v_add_u32_e32 v232, 0xffffffd0, v224
	v_min_u32_e32 v232, 0x400, v232
	v_lshl_add_u32 v232, v232, 2, v173
	ds_read_b32 v219, v232
	v_add_u32_e32 v232, 0xffffffc0, v224
	v_min_u32_e32 v232, 0x400, v232
	v_lshl_add_u32 v232, v232, 2, v173
	ds_read_b32 v220, v232
	v_add_u32_e32 v232, 0xffffffb0, v224
	v_min_u32_e32 v232, 0x400, v232
	v_lshl_add_u32 v232, v232, 2, v173
	ds_read_b32 v221, v232
	v_add_u32_e32 v232, 0xffffffa0, v224
	v_min_u32_e32 v232, 0x400, v232
	v_lshl_add_u32 v232, v232, 2, v173
	ds_read_b32 v222, v232
	v_add_u32_e32 v232, 0xffffff90, v224
	v_min_u32_e32 v232, 0x400, v232
	v_lshl_add_u32 v232, v232, 2, v173
	ds_read_b32 v223, v232
	s_waitcnt lgkmcnt(7)
	v_add_u32_e32 v232, 0x0, v224
	v_cmp_le_i32_e32 vcc, 0, v232
	s_nop 1
	v_cndmask_b32_e32 v216, v252, v216, vcc
	v_add_f32_e32 v18, v18, v216
	s_waitcnt lgkmcnt(6)
	v_add_u32_e32 v232, 0xfffffff0, v224
	v_cmp_le_i32_e32 vcc, 0, v232
	s_nop 1
	v_cndmask_b32_e32 v217, v252, v217, vcc
	v_add_f32_e32 v19, v19, v217
	s_waitcnt lgkmcnt(5)
	v_add_u32_e32 v232, 0xffffffe0, v224
	v_cmp_le_i32_e32 vcc, 0, v232
	s_nop 1
	v_cndmask_b32_e32 v218, v252, v218, vcc
	v_add_f32_e32 v20, v20, v218
	s_waitcnt lgkmcnt(4)
	v_add_u32_e32 v232, 0xffffffd0, v224
	v_cmp_le_i32_e32 vcc, 0, v232
	s_nop 1
	v_cndmask_b32_e32 v219, v252, v219, vcc
	v_add_f32_e32 v21, v21, v219
	s_waitcnt lgkmcnt(3)
	v_add_u32_e32 v232, 0xffffffc0, v224
	v_cmp_le_i32_e32 vcc, 0, v232
	s_nop 1
	v_cndmask_b32_e32 v220, v252, v220, vcc
	v_add_f32_e32 v22, v22, v220
	s_waitcnt lgkmcnt(2)
	v_add_u32_e32 v232, 0xffffffb0, v224
	v_cmp_le_i32_e32 vcc, 0, v232
	s_nop 1
	v_cndmask_b32_e32 v221, v252, v221, vcc
	v_add_f32_e32 v23, v23, v221
	s_waitcnt lgkmcnt(1)
	v_add_u32_e32 v232, 0xffffffa0, v224
	v_cmp_le_i32_e32 vcc, 0, v232
	s_nop 1
	v_cndmask_b32_e32 v222, v252, v222, vcc
	v_add_f32_e32 v24, v24, v222
	s_waitcnt lgkmcnt(0)
	v_add_u32_e32 v232, 0xffffff90, v224
	v_cmp_le_i32_e32 vcc, 0, v232
	s_nop 1
	v_cndmask_b32_e32 v223, v252, v223, vcc
	v_add_f32_e32 v25, v25, v223
	v_add_u32_e32 v232, 0xfffffe00, v224
	v_min_u32_e32 v232, 0x400, v232
	v_lshl_add_u32 v232, v232, 2, v173
	ds_read_b32 v216, v232
	v_add_u32_e32 v232, 0xfffffdf0, v224
	v_min_u32_e32 v232, 0x400, v232
	v_lshl_add_u32 v232, v232, 2, v173
	ds_read_b32 v217, v232
	v_add_u32_e32 v232, 0xfffffde0, v224
	v_min_u32_e32 v232, 0x400, v232
	v_lshl_add_u32 v232, v232, 2, v173
	ds_read_b32 v218, v232
	v_add_u32_e32 v232, 0xfffffdd0, v224
	v_min_u32_e32 v232, 0x400, v232
	v_lshl_add_u32 v232, v232, 2, v173
	ds_read_b32 v219, v232
	v_add_u32_e32 v232, 0xfffffdc0, v224
	v_min_u32_e32 v232, 0x400, v232
	v_lshl_add_u32 v232, v232, 2, v173
	ds_read_b32 v220, v232
	v_add_u32_e32 v232, 0xfffffdb0, v224
	v_min_u32_e32 v232, 0x400, v232
	v_lshl_add_u32 v232, v232, 2, v173
	ds_read_b32 v221, v232
	v_add_u32_e32 v232, 0xfffffda0, v224
	v_min_u32_e32 v232, 0x400, v232
	v_lshl_add_u32 v232, v232, 2, v173
	ds_read_b32 v222, v232
	v_add_u32_e32 v232, 0xfffffd90, v224
	v_min_u32_e32 v232, 0x400, v232
	v_lshl_add_u32 v232, v232, 2, v173
	ds_read_b32 v223, v232
	s_waitcnt lgkmcnt(7)
	v_add_u32_e32 v232, 0xfffffe00, v224
	v_cmp_le_i32_e32 vcc, 0, v232
	s_nop 1
	v_cndmask_b32_e32 v216, v252, v216, vcc
	v_add_f32_e32 v26, v26, v216
	s_waitcnt lgkmcnt(6)
	v_add_u32_e32 v232, 0xfffffdf0, v224
	v_cmp_le_i32_e32 vcc, 0, v232
	s_nop 1
	v_cndmask_b32_e32 v217, v252, v217, vcc
	v_add_f32_e32 v27, v27, v217
	s_waitcnt lgkmcnt(5)
	v_add_u32_e32 v232, 0xfffffde0, v224
	v_cmp_le_i32_e32 vcc, 0, v232
	s_nop 1
	v_cndmask_b32_e32 v218, v252, v218, vcc
	v_add_f32_e32 v28, v28, v218
	s_waitcnt lgkmcnt(4)
	v_add_u32_e32 v232, 0xfffffdd0, v224
	v_cmp_le_i32_e32 vcc, 0, v232
	s_nop 1
	v_cndmask_b32_e32 v219, v252, v219, vcc
	v_add_f32_e32 v29, v29, v219
	s_waitcnt lgkmcnt(3)
	v_add_u32_e32 v232, 0xfffffdc0, v224
	v_cmp_le_i32_e32 vcc, 0, v232
	s_nop 1
	v_cndmask_b32_e32 v220, v252, v220, vcc
	v_add_f32_e32 v30, v30, v220
	s_waitcnt lgkmcnt(2)
	v_add_u32_e32 v232, 0xfffffdb0, v224
	v_cmp_le_i32_e32 vcc, 0, v232
	s_nop 1
	v_cndmask_b32_e32 v221, v252, v221, vcc
	v_add_f32_e32 v31, v31, v221
	s_waitcnt lgkmcnt(1)
	v_add_u32_e32 v232, 0xfffffda0, v224
	v_cmp_le_i32_e32 vcc, 0, v232
	s_nop 1
	v_cndmask_b32_e32 v222, v252, v222, vcc
	v_add_f32_e32 v32, v32, v222
	s_waitcnt lgkmcnt(0)
	v_add_u32_e32 v232, 0xfffffd90, v224
	v_cmp_le_i32_e32 vcc, 0, v232
	s_nop 1
	v_cndmask_b32_e32 v223, v252, v223, vcc
	v_add_f32_e32 v33, v33, v223
	v_exp_f32_e32 v18, v18
	v_exp_f32_e32 v19, v19
	v_exp_f32_e32 v20, v20
	v_exp_f32_e32 v21, v21
	v_exp_f32_e32 v22, v22
	v_exp_f32_e32 v23, v23
	v_exp_f32_e32 v24, v24
	v_exp_f32_e32 v25, v25
	v_exp_f32_e32 v26, v26
	v_exp_f32_e32 v27, v27
	v_exp_f32_e32 v28, v28
	v_exp_f32_e32 v29, v29
	v_exp_f32_e32 v30, v30
	v_exp_f32_e32 v31, v31
	v_exp_f32_e32 v32, v32
	v_exp_f32_e32 v33, v33
	v_add_f32_e32 v18, v18, v19
	v_add_f32_e32 v20, v20, v21
	v_add_f32_e32 v22, v22, v23
	v_add_f32_e32 v24, v24, v25
	v_add_f32_e32 v26, v26, v27
	v_add_f32_e32 v28, v28, v29
	v_add_f32_e32 v30, v30, v31
	v_add_f32_e32 v32, v32, v33
	v_add_f32_e32 v18, v18, v20
	v_add_f32_e32 v22, v22, v24
	v_add_f32_e32 v26, v26, v28
	v_add_f32_e32 v30, v30, v32
	v_add_f32_e32 v18, v18, v22
	v_add_f32_e32 v26, v26, v30
	v_add_f32_e32 v18, v18, v26
	v_add_f32_e32 v170, v170, v18

; #define LAS __attribute__((address_space(3)))
; __device__ __forceinline__ float ex2(float x) { return __builtin_amdgcn_exp2f(x); }
; __device__ __forceinline__ void cmp_sm1(const f32x4 (&sc)[4], int gr, int t0, const LAS float* bt, float (&ls)[4], int r16) {
; #pragma unroll
;     for (int cc = 0; cc < 4; ++cc) {
;         const int cend = (gr * 64 + cc * 16 + r16) * 16 + 31;
; #pragma unroll
;         for (int i = 0; i < 4; ++i) { const int dist = t0 + i - cend; ls[i] += dist >= 0 ? ex2(sc[cc][i] + bt[clampd(dist)]) : 0.f; }
;     }
; }
; __device__ __forceinline__ void nsa_quad_pre(int bg, int quad, const bf16_t* Q, const bf16_t* KV, const bf16_t* KCMP, const bf16_t* VCMPT, const float* GN, bf16_t* ONSA, ...
;     ...
;     if (ngr > 0) {
;         float ls[4] = {0.f, 0.f, 0.f, 0.f};
;         load_k(KF, KP_C(0));
;         for (int gr = 0; gr < ngr; ++gr) {
;             qk_scores(KF, qf, sc);
;             load_k(KF, KP_C(gr + 1 < ngr ? gr + 1 : 0));
;             cmp_sm1(sc, gr, t0, bt, ls, r16);
;         }
.Lcmp_top_q1p1:
	s_nop 1
	s_cmp_lt_i32 s57, s52
	s_cbranch_scc0 .Lcmp_gen_q1p1
	s_waitcnt vmcnt(0)
	v_mov_b32_e32 v228, v225
	v_mov_b32_e32 v229, v225
	v_mov_b32_e32 v230, v225
	v_mov_b32_e32 v231, v225
	s_nop 1
	v_mfma_f32_16x16x32_bf16 v[18:21], v[50:53], v[42:45], v[228:231]
	v_mfma_f32_16x16x32_bf16 v[18:21], v[54:57], v[46:49], v[18:21]
	v_mfma_f32_16x16x32_bf16 v[22:25], v[58:61], v[42:45], v[228:231]
	v_mfma_f32_16x16x32_bf16 v[22:25], v[62:65], v[46:49], v[22:25]
	v_mfma_f32_16x16x32_bf16 v[26:29], v[66:69], v[42:45], v[228:231]
	v_mfma_f32_16x16x32_bf16 v[26:29], v[70:73], v[46:49], v[26:29]
	v_mfma_f32_16x16x32_bf16 v[30:33], v[74:77], v[42:45], v[228:231]
	v_mfma_f32_16x16x32_bf16 v[30:33], v[78:81], v[46:49], v[30:33]
	s_add_i32 s1, s57, 1
	s_cmp_lt_i32 s1, s53
	s_cselect_b32 s1, s1, 0
	s_lshl_b32 s0, s1, 13
	s_add_u32 s70, s66, s0
	s_addc_u32 s71, s67, 0
	global_load_dwordx4 v[50:53], v174, s[70:71] offset:0
	global_load_dwordx4 v[54:57], v174, s[70:71] offset:64
	global_load_dwordx4 v[58:61], v174, s[70:71] offset:512
	global_load_dwordx4 v[62:65], v174, s[70:71] offset:576
	global_load_dwordx4 v[66:69], v175, s[70:71] offset:0
	global_load_dwordx4 v[70:73], v175, s[70:71] offset:64
	global_load_dwordx4 v[74:77], v175, s[70:71] offset:512
	global_load_dwordx4 v[78:81], v175, s[70:71] offset:576
	v_exp_f32_e32 v18, v18
	v_exp_f32_e32 v19, v19
	v_exp_f32_e32 v20, v20
	v_exp_f32_e32 v21, v21
	v_exp_f32_e32 v22, v22
	v_exp_f32_e32 v23, v23
	v_exp_f32_e32 v24, v24
	v_exp_f32_e32 v25, v25
	v_exp_f32_e32 v26, v26
	v_exp_f32_e32 v27, v27
	v_exp_f32_e32 v28, v28
	v_exp_f32_e32 v29, v29
	v_exp_f32_e32 v30, v30
	v_exp_f32_e32 v31, v31
	v_exp_f32_e32 v32, v32
	v_exp_f32_e32 v33, v33
	v_add_f32_e32 v18, v18, v19
	v_add_f32_e32 v20, v20, v21
	v_add_f32_e32 v22, v22, v23
	v_add_f32_e32 v24, v24, v25
	v_add_f32_e32 v26, v26, v27
	v_add_f32_e32 v28, v28, v29
	v_add_f32_e32 v30, v30, v31
	v_add_f32_e32 v32, v32, v33
	v_add_f32_e32 v18, v18, v20
	v_add_f32_e32 v22, v22, v24
	v_add_f32_e32 v26, v26, v28
	v_add_f32_e32 v30, v30, v32
	v_add_f32_e32 v18, v18, v22
	v_add_f32_e32 v26, v26, v30
	v_add_f32_e32 v18, v18, v26
	v_add_f32_e32 v170, v170, v18
	s_branch .Lcmp_nx_q1p1
; #define LAS __attribute__((address_space(3)))
; __device__ __forceinline__ float ex2(float x) { return __builtin_amdgcn_exp2f(x); }
; __device__ __forceinline__ void cmp_sm1(const f32x4 (&sc)[4], int gr, int t0, const LAS float* bt, float (&ls)[4], int r16) {
; #pragma unroll
;     for (int cc = 0; cc < 4; ++cc) {
;         const int cend = (gr * 64 + cc * 16 + r16) * 16 + 31;
; #pragma unroll
;         for (int i = 0; i < 4; ++i) { const int dist = t0 + i - cend; ls[i] += dist >= 0 ? ex2(sc[cc][i] + bt[clampd(dist)]) : 0.f; }
;     }
; }
; __device__ __forceinline__ void nsa_quad_pre(int bg, int quad, const bf16_t* Q, const bf16_t* KV, const bf16_t* KCMP, const bf16_t* VCMPT, const float* GN, bf16_t* ONSA, ...
;     ...
;     if (ngr > 0) {
;         float ls[4] = {0.f, 0.f, 0.f, 0.f};
;         load_k(KF, KP_C(0));
;         for (int gr = 0; gr < ngr; ++gr) {
;             qk_scores(KF, qf, sc);
;             load_k(KF, KP_C(gr + 1 < ngr ? gr + 1 : 0));
;             cmp_sm1(sc, gr, t0, bt, ls, r16);
;         }
.Lcmp_gen_q1p1:
	s_nop 1
	s_waitcnt vmcnt(0)
	v_mfma_f32_16x16x32_bf16 v[18:21], v[50:53], v[42:45], 0
	v_mfma_f32_16x16x32_bf16 v[18:21], v[54:57], v[46:49], v[18:21]
	v_mfma_f32_16x16x32_bf16 v[22:25], v[58:61], v[42:45], 0
	v_mfma_f32_16x16x32_bf16 v[22:25], v[62:65], v[46:49], v[22:25]
	v_mfma_f32_16x16x32_bf16 v[26:29], v[66:69], v[42:45], 0
	v_mfma_f32_16x16x32_bf16 v[26:29], v[70:73], v[46:49], v[26:29]
	v_mfma_f32_16x16x32_bf16 v[30:33], v[74:77], v[42:45], 0
	v_mfma_f32_16x16x32_bf16 v[30:33], v[78:81], v[46:49], v[30:33]
	s_add_i32 s1, s57, 1
	s_cmp_lt_i32 s1, s53
	s_cselect_b32 s1, s1, 0
	s_lshl_b32 s0, s1, 13
	s_add_u32 s70, s66, s0
	s_addc_u32 s71, s67, 0
	global_load_dwordx4 v[50:53], v174, s[70:71] offset:0
	global_load_dwordx4 v[54:57], v174, s[70:71] offset:64
	global_load_dwordx4 v[58:61], v174, s[70:71] offset:512
	global_load_dwordx4 v[62:65], v174, s[70:71] offset:576
	global_load_dwordx4 v[66:69], v175, s[70:71] offset:0
	global_load_dwordx4 v[70:73], v175, s[70:71] offset:64
	global_load_dwordx4 v[74:77], v175, s[70:71] offset:512
	global_load_dwordx4 v[78:81], v175, s[70:71] offset:576
	s_lshl_b32 s0, s57, 10
	v_subrev_u32_e32 v224, s0, v99
	v_add_u32_e32 v232, 0x0, v224
	v_min_u32_e32 v232, 0x400, v232
	v_lshl_add_u32 v232, v232, 2, v173
	ds_read_b32 v216, v232
	v_add_u32_e32 v232, 0xfffffff0, v224
	v_min_u32_e32 v232, 0x400, v232
	v_lshl_add_u32 v232, v232, 2, v173
	ds_read_b32 v217, v232
	v_add_u32_e32 v232, 0xffffffe0, v224
	v_min_u32_e32 v232, 0x400, v232
	v_lshl_add_u32 v232, v232, 2, v173
	ds_read_b32 v218, v232
	v_add_u32_e32 v232, 0xffffffd0, v224
	v_min_u32_e32 v232, 0x400, v232
	v_lshl_add_u32 v232, v232, 2, v173
	ds_read_b32 v219, v232
	v_add_u32_e32 v232, 0xffffffc0, v224
	v_min_u32_e32 v232, 0x400, v232
	v_lshl_add_u32 v232, v232, 2, v173
	ds_read_b32 v220, v232
	v_add_u32_e32 v232, 0xffffffb0, v224
	v_min_u32_e32 v232, 0x400, v232
	v_lshl_add_u32 v232, v232, 2, v173
	ds_read_b32 v221, v232
	v_add_u32_e32 v232, 0xffffffa0, v224
	v_min_u32_e32 v232, 0x400, v232
	v_lshl_add_u32 v232, v232, 2, v173
	ds_read_b32 v222, v232
	v_add_u32_e32 v232, 0xffffff90, v224
	v_min_u32_e32 v232, 0x400, v232
	v_lshl_add_u32 v232, v232, 2, v173
	ds_read_b32 v223, v232
	s_waitcnt lgkmcnt(7)
	v_add_u32_e32 v232, 0x0, v224
	v_cmp_le_i32_e32 vcc, 0, v232
	s_nop 1
	v_cndmask_b32_e32 v216, v252, v216, vcc
	v_add_f32_e32 v18, v18, v216
	s_waitcnt lgkmcnt(6)
	v_add_u32_e32 v232, 0xfffffff0, v224
	v_cmp_le_i32_e32 vcc, 0, v232
	s_nop 1
	v_cndmask_b32_e32 v217, v252, v217, vcc
	v_add_f32_e32 v19, v19, v217
	s_waitcnt lgkmcnt(5)
	v_add_u32_e32 v232, 0xffffffe0, v224
	v_cmp_le_i32_e32 vcc, 0, v232
	s_nop 1
	v_cndmask_b32_e32 v218, v252, v218, vcc
	v_add_f32_e32 v20, v20, v218
	s_waitcnt lgkmcnt(4)
	v_add_u32_e32 v232, 0xffffffd0, v224
	v_cmp_le_i32_e32 vcc, 0, v232
	s_nop 1
	v_cndmask_b32_e32 v219, v252, v219, vcc
	v_add_f32_e32 v21, v21, v219
	s_waitcnt lgkmcnt(3)
	v_add_u32_e32 v232, 0xffffffc0, v224
	v_cmp_le_i32_e32 vcc, 0, v232
	s_nop 1
	v_cndmask_b32_e32 v220, v252, v220, vcc
	v_add_f32_e32 v22, v22, v220
	s_waitcnt lgkmcnt(2)
	v_add_u32_e32 v232, 0xffffffb0, v224
	v_cmp_le_i32_e32 vcc, 0, v232
	s_nop 1
	v_cndmask_b32_e32 v221, v252, v221, vcc
	v_add_f32_e32 v23, v23, v221
	s_waitcnt lgkmcnt(1)
	v_add_u32_e32 v232, 0xffffffa0, v224
	v_cmp_le_i32_e32 vcc, 0, v232
	s_nop 1
	v_cndmask_b32_e32 v222, v252, v222, vcc
	v_add_f32_e32 v24, v24, v222
	s_waitcnt lgkmcnt(0)
	v_add_u32_e32 v232, 0xffffff90, v224
	v_cmp_le_i32_e32 vcc, 0, v232
	s_nop 1
	v_cndmask_b32_e32 v223, v252, v223, vcc
	v_add_f32_e32 v25, v25, v223
	v_add_u32_e32 v232, 0xfffffe00, v224
	v_min_u32_e32 v232, 0x400, v232
	v_lshl_add_u32 v232, v232, 2, v173
	ds_read_b32 v216, v232
	v_add_u32_e32 v232, 0xfffffdf0, v224
	v_min_u32_e32 v232, 0x400, v232
	v_lshl_add_u32 v232, v232, 2, v173
	ds_read_b32 v217, v232
	v_add_u32_e32 v232, 0xfffffde0, v224
	v_min_u32_e32 v232, 0x400, v232
	v_lshl_add_u32 v232, v232, 2, v173
	ds_read_b32 v218, v232
	v_add_u32_e32 v232, 0xfffffdd0, v224
	v_min_u32_e32 v232, 0x400, v232
	v_lshl_add_u32 v232, v232, 2, v173
	ds_read_b32 v219, v232
	v_add_u32_e32 v232, 0xfffffdc0, v224
	v_min_u32_e32 v232, 0x400, v232
	v_lshl_add_u32 v232, v232, 2, v173
	ds_read_b32 v220, v232
	v_add_u32_e32 v232, 0xfffffdb0, v224
	v_min_u32_e32 v232, 0x400, v232
	v_lshl_add_u32 v232, v232, 2, v173
	ds_read_b32 v221, v232
	v_add_u32_e32 v232, 0xfffffda0, v224
	v_min_u32_e32 v232, 0x400, v232
	v_lshl_add_u32 v232, v232, 2, v173
	ds_read_b32 v222, v232
	v_add_u32_e32 v232, 0xfffffd90, v224
	v_min_u32_e32 v232, 0x400, v232
	v_lshl_add_u32 v232, v232, 2, v173
	ds_read_b32 v223, v232
	s_waitcnt lgkmcnt(7)
	v_add_u32_e32 v232, 0xfffffe00, v224
	v_cmp_le_i32_e32 vcc, 0, v232
	s_nop 1
	v_cndmask_b32_e32 v216, v252, v216, vcc
	v_add_f32_e32 v26, v26, v216
	s_waitcnt lgkmcnt(6)
	v_add_u32_e32 v232, 0xfffffdf0, v224
	v_cmp_le_i32_e32 vcc, 0, v232
	s_nop 1
	v_cndmask_b32_e32 v217, v252, v217, vcc
	v_add_f32_e32 v27, v27, v217
	s_waitcnt lgkmcnt(5)
	v_add_u32_e32 v232, 0xfffffde0, v224
	v_cmp_le_i32_e32 vcc, 0, v232
	s_nop 1
	v_cndmask_b32_e32 v218, v252, v218, vcc
	v_add_f32_e32 v28, v28, v218
	s_waitcnt lgkmcnt(4)
	v_add_u32_e32 v232, 0xfffffdd0, v224
	v_cmp_le_i32_e32 vcc, 0, v232
	s_nop 1
	v_cndmask_b32_e32 v219, v252, v219, vcc
	v_add_f32_e32 v29, v29, v219
	s_waitcnt lgkmcnt(3)
	v_add_u32_e32 v232, 0xfffffdc0, v224
	v_cmp_le_i32_e32 vcc, 0, v232
	s_nop 1
	v_cndmask_b32_e32 v220, v252, v220, vcc
	v_add_f32_e32 v30, v30, v220
	s_waitcnt lgkmcnt(2)
	v_add_u32_e32 v232, 0xfffffdb0, v224
	v_cmp_le_i32_e32 vcc, 0, v232
	s_nop 1
	v_cndmask_b32_e32 v221, v252, v221, vcc
	v_add_f32_e32 v31, v31, v221
	s_waitcnt lgkmcnt(1)
	v_add_u32_e32 v232, 0xfffffda0, v224
	v_cmp_le_i32_e32 vcc, 0, v232
	s_nop 1
	v_cndmask_b32_e32 v222, v252, v222, vcc
	v_add_f32_e32 v32, v32, v222
	s_waitcnt lgkmcnt(0)
	v_add_u32_e32 v232, 0xfffffd90, v224
	v_cmp_le_i32_e32 vcc, 0, v232
	s_nop 1
	v_cndmask_b32_e32 v223, v252, v223, vcc
	v_add_f32_e32 v33, v33, v223
	v_exp_f32_e32 v18, v18
	v_exp_f32_e32 v19, v19
	v_exp_f32_e32 v20, v20
	v_exp_f32_e32 v21, v21
	v_exp_f32_e32 v22, v22
	v_exp_f32_e32 v23, v23
	v_exp_f32_e32 v24, v24
	v_exp_f32_e32 v25, v25
	v_exp_f32_e32 v26, v26
	v_exp_f32_e32 v27, v27
	v_exp_f32_e32 v28, v28
	v_exp_f32_e32 v29, v29
	v_exp_f32_e32 v30, v30
	v_exp_f32_e32 v31, v31
	v_exp_f32_e32 v32, v32
	v_exp_f32_e32 v33, v33
	v_add_f32_e32 v18, v18, v19
	v_add_f32_e32 v20, v20, v21
	v_add_f32_e32 v22, v22, v23
	v_add_f32_e32 v24, v24, v25
	v_add_f32_e32 v26, v26, v27
	v_add_f32_e32 v28, v28, v29
	v_add_f32_e32 v30, v30, v31
	v_add_f32_e32 v32, v32, v33
	v_add_f32_e32 v18, v18, v20
	v_add_f32_e32 v22, v22, v24
	v_add_f32_e32 v26, v26, v28
	v_add_f32_e32 v30, v30, v32
	v_add_f32_e32 v18, v18, v22
	v_add_f32_e32 v26, v26, v30
	v_add_f32_e32 v18, v18, v26
	v_add_f32_e32 v170, v170, v18

; #define LAS __attribute__((address_space(3)))
; #define NSA_LD1(jj) do { kr = *(const bf16x8*)((const char*)Kt + (size_t)(jj) * 8192 + kgo); vr = *(const bf16x8*)((const char*)Vt + (jj) * 128 + vgo); } while (0)
; template <int MODE> ...
;     const int r16 = lane & 15, q4 = lane >> 4, b = bg >> 2, g = bg & 3;
;     const bf16_t* Kt = KV + (MODE ? 4 : 2) * (size_t)MTOK * 256 + (size_t)bg * SEQ * 64; const bf16_t* Vt = KV + (MODE ? 5 : 3) * (size_t)MTOK * 256 + (size_t)bg * 64 * SEQ;
;     const LAS float* bt = btab + q4 * 1028;
;     const float bfar = bt[1024];
;     const f32x4 z4 = {0.f, 0.f, 0.f, 0.f};
;     const int j0 = MODE ? (qb - 8 > 0 ? qb - 8 : 0) : 0;
;     if (MODE == 0 && tid < 256) { const int tok = tid >> 2, word = tid & 3; unsigned m = 0u;
;         if (qb < 16) m = word == 0 ? ((2u << qb) - 1u) : 0u;
;         else {
; #pragma unroll
;             for (int n = 0; n < 16; ++n) { const int j = selall[tok * 16 + n]; m |= ((j >> 5) == word) ? (1u << (j & 31)) : 0u; } }
;         masks[tid] = m; }
;     ...
;     for (int jA = j0, pp = 0; jA <= qb; jA += 2, pp ^= 1) {
;       for (int sub = 0; sub < 2; ++sub) {
;         const int j = jA + sub; if (j > qb) break;
;         const bool pre = j + 2 <= qb;
;         if (pre) NSA_LD1(j + 2);
;         const LAS bf16_t* Ks = stage + pp * 18432 + sub * 9216; const LAS bf16_t* Vs = Ks + 4608;
;         const bool far = MODE == 0 && (qb - j >= 17);
.Lnsa_mode_top:
	s_nop 1
	s_cmp_lg_u32 s54, 0
	s_cbranch_scc1 .Lnsa_pwin_4
	s_mov_b32 s53, 16
	s_mov_b32 s52, 0x80000000
	v_min_u32_e32 v228, 11, v184
	v_lshlrev_b32_e32 v228, 2, v228
	s_lshl_b32 s0, s80, 2
	s_add_i32 s1, s0, 130112
	v_add_u32_e32 v229, s1, v228
	v_add_u32_e32 v228, 0x1fc40, v228
	v_cmp_gt_u32_e32 vcc, 4, v184
	s_nop 1
	v_cndmask_b32_e32 v228, v229, v228, vcc
	ds_read_b32 v179, v228
	v_and_b32_e32 v178, 3, v184
	v_add_u32_e32 v178, s80, v178
	v_lshlrev_b32_e32 v178, 4, v178
	v_add_u32_e32 v178, 0xd840, v178
	s_waitcnt lgkmcnt(0)
	s_branch .Lnsa_pjoin_5
.Lnsa_pwin_4:
	s_nop 1
	s_mov_b32 s53, 8
	s_mov_b32 s52, 512
	s_add_i32 s0, s18, -8
	s_max_i32 s0, s0, 0
	v_and_b32_e32 v228, 3, v184
	v_lshlrev_b32_e32 v228, 5, v228
	v_sub_u32_e32 v229, s0, v228
	v_max_i32_e32 v229, 0, v229
	v_sub_u32_e32 v230, s18, v228
	v_min_i32_e32 v230, 31, v230
	v_sub_u32_e32 v253, v230, v229
	v_add_u32_e32 v253, 1, v253
	v_max_i32_e32 v230, 0, v253
	v_min_i32_e32 v230, 31, v230
	v_bfm_b32 v179, v230, v229
	v_cmp_lt_i32_e32 vcc, 0, v253
	s_nop 1
	v_cndmask_b32_e32 v179, 0, v179, vcc
	v_cmp_gt_u32_e32 vcc, 32, v229
	s_nop 1
	v_cndmask_b32_e32 v179, 0, v179, vcc
	v_mov_b32_e32 v232, -1
	v_mov_b32_e32 v233, -1
.Lnsa_pjoin_5:
	s_nop 1
	s_mov_b32 s21, -1
	v_readlane_b32 s72, v179, 0
	v_readlane_b32 s73, v179, 1
	v_readlane_b32 s74, v179, 2
	v_readlane_b32 s75, v179, 3
	v_readlane_b32 s66, v179, 4
	v_readlane_b32 s67, v179, 5
	v_readlane_b32 s68, v179, 6
	v_readlane_b32 s69, v179, 7
	v_readlane_b32 s70, v179, 8
	v_readlane_b32 s71, v179, 9
	v_readlane_b32 s94, v179, 10
	v_readlane_b32 s95, v179, 11
	s_bcnt1_i32_b64 s14, s[72:73]
	s_bcnt1_i32_b64 s92, s[74:75]
	s_add_i32 s92, s92, s14
	s_add_i32 s19, s92, -1
	s_lshl_b32 s15, s80, 6
	s_add_i32 s15, s15, 16448
	v_mov_b32_e32 v253, 0x100
	v_mov_b32_e32 v231, 0x200
	v_mov_b32_e32 v229, v184
	v_cndmask_b32_e64 v230, 0, v253, s[66:67]
	v_or_b32_e32 v230, v230, v229
	v_cndmask_b32_e64 v228, 0, v231, s[70:71]
	v_or_b32_e32 v230, v230, v228
	v_sub_u32_e32 v228, s18, v229
	v_mov_b32_e32 v227, 0x400
	v_cmp_eq_u32_e32 vcc, 0, v228
	s_nop 1
	v_cndmask_b32_e32 v229, 0, v227, vcc
	v_or_b32_e32 v230, v230, v229
	v_cmp_eq_u32_e32 vcc, s53, v228
	s_nop 1
	v_cndmask_b32_e32 v229, 0, v227, vcc
	v_or_b32_e32 v230, v230, v229
	v_mov_b32_e32 v227, 0x800
	v_cmp_lt_i32_e32 vcc, 16, v228
	s_nop 1
	v_cndmask_b32_e32 v229, 0, v227, vcc
	v_or_b32_e32 v230, v230, v229
	v_mbcnt_lo_u32_b32 v229, s72, 0
	v_mbcnt_hi_u32_b32 v229, s73, v229
	v_lshl_add_u32 v229, v229, 2, s15
	s_mov_b64 exec, s[72:73]
	ds_write_b32 v229, v230
	s_mov_b64 exec, -1
	v_add_u32_e32 v229, 64, v184
	v_cndmask_b32_e64 v230, 0, v253, s[68:69]
	v_or_b32_e32 v230, v230, v229
	v_cndmask_b32_e64 v228, 0, v231, s[94:95]
	v_or_b32_e32 v230, v230, v228
	v_sub_u32_e32 v228, s18, v229
	v_mov_b32_e32 v227, 0x400
	v_cmp_eq_u32_e32 vcc, 0, v228
	s_nop 1
	v_cndmask_b32_e32 v229, 0, v227, vcc
	v_or_b32_e32 v230, v230, v229
	v_cmp_eq_u32_e32 vcc, s53, v228
	s_nop 1
	v_cndmask_b32_e32 v229, 0, v227, vcc
	v_or_b32_e32 v230, v230, v229
	v_mov_b32_e32 v227, 0x800
	v_cmp_lt_i32_e32 vcc, 16, v228
	s_nop 1
	v_cndmask_b32_e32 v229, 0, v227, vcc
	v_or_b32_e32 v230, v230, v229
	v_mbcnt_lo_u32_b32 v229, s74, 0
	v_mbcnt_hi_u32_b32 v229, s75, v229
	v_add_u32_e32 v229, s14, v229
	v_lshl_add_u32 v229, v229, 2, s15
	s_mov_b64 exec, s[74:75]
	ds_write_b32 v229, v230
	s_mov_b64 exec, -1
	v_lshl_add_u32 v229, v184, 2, s15
	s_waitcnt lgkmcnt(0)
	ds_read_b32 v179, v229
	ds_read_b32 v228, v229 offset:256
	s_cmp_lg_u32 s54, 0
	s_cbranch_scc1 .Lnsa_kvwin_6
	s_add_u32 s66, s30, 0x33900000
	s_addc_u32 s67, s31, 0
	s_add_u32 s68, s30, 0x34900000
	s_addc_u32 s69, s31, 0
	s_branch .Lnsa_kvj_7
.Lnsa_kvwin_6:
	s_add_u32 s66, s30, 0x35900000
	s_addc_u32 s67, s31, 0
	s_add_u32 s68, s30, 0x36900000
	s_addc_u32 s69, s31, 0
; #define LAS __attribute__((address_space(3)))
; #define MFMA16(a, b, c) __builtin_amdgcn_mfma_f32_16x16x32_bf16(a, b, c, 0, 0, 0)
; #define NSA_LD1(jj) do { kr = *(const bf16x8*)((const char*)Kt + (size_t)(jj) * 8192 + kgo); vr = *(const bf16x8*)((const char*)Vt + (jj) * 128 + vgo); } while (0)
; #define NSA_ST1(st_, half_) do { LAS bf16_t* nx_ = stage + (st_) * 18432 + (half_) * 9216 + soff; *(LAS bf16x8*)nx_ = kr; *(LAS bf16x8*)(nx_ + 4608) = vr; } while (0)
; template <int MODE> ...
;     ...
;     bf16x8 kr, vr;
;     NSA_LD1(j0); NSA_ST1(0, 0);
;     if (j0 + 1 <= qb) { NSA_LD1(j0 + 1); NSA_ST1(0, 1); }
;     __syncthreads();
;     for (int jA = j0, pp = 0; jA <= qb; jA += 2, pp ^= 1) {
;       for (int sub = 0; sub < 2; ++sub) {
;         const int j = jA + sub; if (j > qb) break;
;         const bool pre = j + 2 <= qb;
;         if (pre) NSA_LD1(j + 2);
;         const LAS bf16_t* Ks = stage + pp * 18432 + sub * 9216; const LAS bf16_t* Vs = Ks + 4608;
;         const bool far = MODE == 0 && (qb - j >= 17);
;     ...
;                 for (int ks = 0; ks < 2; ++ks) { const bf16x8 aP = *(const LAS bf16x8*)(Pb + r16 * 72 + ks * 32 + q4 * 8);
; #pragma unroll
;                     for (int nt = 0; nt < 4; ++nt) os[tile][nt] = MFMA16(aP, *(const LAS bf16x8*)(Vs + (nt * 16 + r16) * 72 + ks * 32 + q4 * 8), os[tile][nt]); }
.Lnsa_kvj_7:
	s_lshr_b32 s15, s97, 13
	s_lshl_b32 s15, s15, 2
	s_and_b32 s1, s88, 3
	s_or_b32 s15, s15, s1
	s_lshl_b32 s15, s15, 20
	s_add_u32 s66, s66, s15
	s_addc_u32 s67, s67, 0
	s_add_u32 s68, s68, s15
	s_addc_u32 s69, s69, 0
	s_lshl_b32 s33, s80, 7
	s_add_i32 s33, s33, 56384
	s_mov_b32 s57, 0
	v_mov_b32_e32 v2, 0
	v_mov_b32_e32 v3, 0
	v_mov_b32_e32 v4, 0
	v_mov_b32_e32 v5, 0
	v_mov_b32_e32 v6, 0
	v_mov_b32_e32 v7, 0
	v_mov_b32_e32 v8, 0
	v_mov_b32_e32 v9, 0
	v_mov_b32_e32 v10, 0
	v_mov_b32_e32 v11, 0
	v_mov_b32_e32 v12, 0
	v_mov_b32_e32 v13, 0
	v_mov_b32_e32 v14, 0
	v_mov_b32_e32 v15, 0
	v_mov_b32_e32 v16, 0
	v_mov_b32_e32 v17, 0
	v_mov_b32_e32 v215, 0
	v_mov_b32_e32 v18, 0
	v_mov_b32_e32 v19, 0
	v_mov_b32_e32 v20, 0
	v_mov_b32_e32 v21, 0
	v_mov_b32_e32 v22, 0
	v_mov_b32_e32 v23, 0
	v_mov_b32_e32 v24, 0
	v_mov_b32_e32 v25, 0
	v_mov_b32_e32 v26, 0
	v_mov_b32_e32 v27, 0
	v_mov_b32_e32 v28, 0
	v_mov_b32_e32 v29, 0
	v_mov_b32_e32 v30, 0
	v_mov_b32_e32 v31, 0
	v_mov_b32_e32 v32, 0
	v_mov_b32_e32 v33, 0
	v_mov_b32_e32 v224, 0
	s_waitcnt lgkmcnt(0)
	v_readlane_b32 s0, v179, s57
	v_readlane_b32 s1, v228, s57
	s_cmp_lt_u32 s57, 64
	s_cselect_b32 s93, s0, s1
	s_min_u32 s14, 1, s19
	v_readlane_b32 s0, v179, s14
	v_readlane_b32 s1, v228, s14
	s_cmp_lt_u32 s14, 64
	s_cselect_b32 s94, s0, s1
	s_and_b32 s73, s93, 255
	s_and_b32 s0, s57, 3
	s_lshl_b32 s0, s0, 14
	s_add_i32 s0, s0, s33
	s_lshl_b32 s1, s73, 13
	s_add_u32 s70, s66, s1
	s_addc_u32 s71, s67, 0
	s_mov_b32 m0, s0
	s_lshl_b32 s1, s73, 7
	global_load_lds_dwordx4 v174, s[70:71]
	s_add_u32 s70, s68, s1
	s_addc_u32 s71, s69, 0
	s_add_i32 m0, s0, 8192
	s_add_i32 s1, s57, 0
	global_load_lds_dwordx4 v175, s[70:71]
	s_and_b32 s73, s94, 255
	s_mov_b32 s14, 1
	s_and_b32 s0, s14, 3
	s_lshl_b32 s0, s0, 14
	s_add_i32 s0, s0, s33
	s_lshl_b32 s1, s73, 13
	s_add_u32 s70, s66, s1
	s_addc_u32 s71, s67, 0
	s_mov_b32 m0, s0
	s_lshl_b32 s1, s73, 7
	global_load_lds_dwordx4 v174, s[70:71]
	s_add_u32 s70, s68, s1
	s_addc_u32 s71, s69, 0
	s_add_i32 m0, s0, 8192
	s_add_i32 s1, s14, 0
	global_load_lds_dwordx4 v175, s[70:71]
	s_mov_b32 s43, 0
	s_waitcnt vmcnt(2)
	s_barrier
.Lnsa_blk_loop:
	s_add_i32 s14, s57, 2
	s_min_u32 s15, s14, s19
	v_readlane_b32 s0, v179, s15
	v_readlane_b32 s1, v228, s15
	s_cmp_lt_u32 s15, 64
	s_cselect_b32 s95, s0, s1
	s_and_b32 s73, s95, 255
	s_and_b32 s0, s14, 3
	s_lshl_b32 s0, s0, 14
	s_add_i32 s0, s0, s33
	s_lshl_b32 s1, s73, 13
	s_add_u32 s70, s66, s1
	s_addc_u32 s71, s67, 0
	s_mov_b32 m0, s0
	s_lshl_b32 s1, s73, 7
	global_load_lds_dwordx4 v174, s[70:71]
	s_add_u32 s70, s68, s1
	s_addc_u32 s71, s69, 0
	s_add_i32 m0, s0, 8192
	s_add_i32 s1, s14, 0
	global_load_lds_dwordx4 v175, s[70:71]
	s_cmp_eq_u32 s43, 0
	s_cbranch_scc1 .Lnsa_pvnone_8
	ds_read_b128 v[50:53], v172 offset:0
	ds_read_b128 v[54:57], v173 offset:0
	ds_read_b128 v[58:61], v172 offset:2048
	ds_read_b128 v[62:65], v173 offset:2048
	s_cmp_eq_u32 s43, 3
	s_cbranch_scc0 .Lnsa_pvone_9
	s_waitcnt lgkmcnt(2)
	v_mfma_f32_16x16x32_bf16 v[2:5], v[50:53], v[82:85], v[2:5]
	v_mfma_f32_16x16x32_bf16 v[18:21], v[50:53], v[90:93], v[18:21]
	v_mfma_f32_16x16x32_bf16 v[2:5], v[54:57], v[86:89], v[2:5]
	v_mfma_f32_16x16x32_bf16 v[18:21], v[54:57], v[94:97], v[18:21]
	ds_read_b128 v[50:53], v172 offset:4096
	ds_read_b128 v[54:57], v173 offset:4096
	s_waitcnt lgkmcnt(2)
	v_mfma_f32_16x16x32_bf16 v[6:9], v[58:61], v[82:85], v[6:9]
	v_mfma_f32_16x16x32_bf16 v[22:25], v[58:61], v[90:93], v[22:25]
	v_mfma_f32_16x16x32_bf16 v[6:9], v[62:65], v[86:89], v[6:9]
	v_mfma_f32_16x16x32_bf16 v[22:25], v[62:65], v[94:97], v[22:25]
	ds_read_b128 v[58:61], v172 offset:6144
	ds_read_b128 v[62:65], v173 offset:6144
	s_waitcnt lgkmcnt(2)
	v_mfma_f32_16x16x32_bf16 v[10:13], v[50:53], v[82:85], v[10:13]
	v_mfma_f32_16x16x32_bf16 v[26:29], v[50:53], v[90:93], v[26:29]
	v_mfma_f32_16x16x32_bf16 v[10:13], v[54:57], v[86:89], v[10:13]
	v_mfma_f32_16x16x32_bf16 v[26:29], v[54:57], v[94:97], v[26:29]
	s_waitcnt lgkmcnt(0)
	v_mfma_f32_16x16x32_bf16 v[14:17], v[58:61], v[82:85], v[14:17]
	v_mfma_f32_16x16x32_bf16 v[30:33], v[58:61], v[90:93], v[30:33]
	v_mfma_f32_16x16x32_bf16 v[14:17], v[62:65], v[86:89], v[14:17]
	v_mfma_f32_16x16x32_bf16 v[30:33], v[62:65], v[94:97], v[30:33]
	s_branch .Lnsa_pvend_11
.Lnsa_pvone_9:
	s_cmp_eq_u32 s43, 2
	s_cbranch_scc1 .Lnsa_pvt1_10
	s_waitcnt lgkmcnt(2)
	v_mfma_f32_16x16x32_bf16 v[2:5], v[50:53], v[82:85], v[2:5]
	v_mfma_f32_16x16x32_bf16 v[2:5], v[54:57], v[86:89], v[2:5]
	ds_read_b128 v[50:53], v172 offset:4096
	ds_read_b128 v[54:57], v173 offset:4096
	s_waitcnt lgkmcnt(2)
	v_mfma_f32_16x16x32_bf16 v[6:9], v[58:61], v[82:85], v[6:9]
	v_mfma_f32_16x16x32_bf16 v[6:9], v[62:65], v[86:89], v[6:9]
	ds_read_b128 v[58:61], v172 offset:6144
	ds_read_b128 v[62:65], v173 offset:6144
	s_waitcnt lgkmcnt(2)
	v_mfma_f32_16x16x32_bf16 v[10:13], v[50:53], v[82:85], v[10:13]
	v_mfma_f32_16x16x32_bf16 v[10:13], v[54:57], v[86:89], v[10:13]
	s_waitcnt lgkmcnt(0)
	v_mfma_f32_16x16x32_bf16 v[14:17], v[58:61], v[82:85], v[14:17]
	v_mfma_f32_16x16x32_bf16 v[14:17], v[62:65], v[86:89], v[14:17]
	s_branch .Lnsa_pvend_11
.Lnsa_pvt1_10:
	s_waitcnt lgkmcnt(2)
	v_mfma_f32_16x16x32_bf16 v[18:21], v[50:53], v[90:93], v[18:21]
	v_mfma_f32_16x16x32_bf16 v[18:21], v[54:57], v[94:97], v[18:21]
	ds_read_b128 v[50:53], v172 offset:4096
	ds_read_b128 v[54:57], v173 offset:4096
	s_waitcnt lgkmcnt(2)
	v_mfma_f32_16x16x32_bf16 v[22:25], v[58:61], v[90:93], v[22:25]
	v_mfma_f32_16x16x32_bf16 v[22:25], v[62:65], v[94:97], v[22:25]
	ds_read_b128 v[58:61], v172 offset:6144
	ds_read_b128 v[62:65], v173 offset:6144
	s_waitcnt lgkmcnt(2)
	v_mfma_f32_16x16x32_bf16 v[26:29], v[50:53], v[90:93], v[26:29]
	v_mfma_f32_16x16x32_bf16 v[26:29], v[54:57], v[94:97], v[26:29]
	s_waitcnt lgkmcnt(0)
	v_mfma_f32_16x16x32_bf16 v[30:33], v[58:61], v[90:93], v[30:33]
	v_mfma_f32_16x16x32_bf16 v[30:33], v[62:65], v[94:97], v[30:33]

; #define LAS __attribute__((address_space(3)))
; #define MFMA16(a, b, c) __builtin_amdgcn_mfma_f32_16x16x32_bf16(a, b, c, 0, 0, 0)
; __device__ __forceinline__ bf16_t tobf(float x) { return (bf16_t)pk2(x, 0.f); }
; __device__ __forceinline__ float ex2(float x) { return __builtin_amdgcn_exp2f(x); }
; template <int MODE> ...
;     ...
;         const bool far = MODE == 0 && (qb - j >= 17);
; #pragma unroll
;         for (int tile = 0; tile < 2; ++tile) {
;             const int tl0 = wave * 8 + tile * 4, t0 = qb * 64 + tl0;
;             unsigned mb[4] = {1u, 1u, 1u, 1u};
;             if (MODE == 0) {
; #pragma unroll
;                 for (int i = 0; i < 4; ++i) mb[i] = (masks[(tl0 + i) * 4 + (j >> 5)] >> (j & 31)) & 1u; }
;             if (MODE == 1 || __builtin_amdgcn_readfirstlane((int)(mb[0] | mb[1] | mb[2] | mb[3]))) {
;                 f32x4 sc[4];
; #pragma unroll
;                 for (int cc = 0; cc < 4; ++cc) { const LAS bf16_t* kp = Ks + (cc * 16 + r16) * 72 + q4 * 8;
;                     sc[cc] = MFMA16(aq[tile][0], *(const LAS bf16x8*)kp, z4); sc[cc] = MFMA16(aq[tile][1], *(const LAS bf16x8*)(kp + 32), sc[cc]); }
;                 if (far) {
; #pragma unroll
;                     for (int cc = 0; cc < 4; ++cc)
; #pragma unroll
;                         for (int i = 0; i < 4; ++i) { const float p = mb[i] ? ex2(sc[cc][i] + bfar) : 0.f; ls[tile][i] += p; Pb[(4 * q4 + i) * 72 + cc * 16 + r16] = tobf(p); }
;                 } else {
; #pragma unroll
;                     for (int cc = 0; cc < 4; ++cc) { const int pos = j * 64 + cc * 16 + r16;
; #pragma unroll
;                         for (int i = 0; i < 4; ++i) { const int dist = t0 + i - pos; const bool ok = MODE ? ((unsigned)dist < 512u) : (dist >= 0 && mb[i]);
;                             const float p = ok ? ex2(sc[cc][i] + bt[clampd(dist)]) : 0.f; ls[tile][i] += p; Pb[(4 * q4 + i) * 72 + cc * 16 + r16] = tobf(p); } }
.Lnsa_pvnone_8:
	s_and_b32 s73, s93, 255
	s_bfe_u32 s34, s93, 0x20008
	s_bfe_u32 s42, s93, 0x2000a
	s_sub_i32 s47, s18, s73
	s_lshr_b32 s46, s73, 5
	s_and_b32 s72, s73, 31
	s_and_b32 s35, s57, 3
	s_lshl_b32 s35, s35, 14
	v_add_u32_e32 v170, s35, v98
	v_add_u32_e32 v171, v170, v0
	v_add_u32_e32 v172, s35, v99
	v_add_u32_e32 v173, v172, v0
	s_lshl_b32 s0, s47, 6
	v_add_u32_e32 v229, s0, v176
	s_lshl_b32 s0, s47, 8
	v_add_u32_e32 v231, s0, v177
	s_cmp_eq_u32 s46, s21
	s_cbranch_scc1 .Lnsa_mwok_12
	s_mov_b32 s21, s46
	s_cmp_lg_u32 s54, 0
	s_cbranch_scc1 .Lnsa_mwok_12
	s_lshl_b32 s15, s46, 2
	v_add_u32_e32 v230, s15, v178
	ds_read_b32 v232, v230
	ds_read_b32 v233, v230 offset:64
	s_waitcnt lgkmcnt(0)
.Lnsa_mwok_12:
	v_bfe_i32 v234, v232, s72, 1
	v_bfe_i32 v235, v233, s72, 1
	s_mov_b32 s43, s34
	s_cmp_eq_u32 s34, 3
	s_cbranch_scc0 .Lnsa_nopair_13
	s_cmp_eq_u32 s42, 1
	s_cbranch_scc1 .Lnsa_nopair_13
	s_cmp_eq_u32 s42, 2
	s_cbranch_scc1 .Lnsa_pfar_16
	v_add_u32_e32 v230, 16, v231
	v_bfi_b32 v253, v234, v231, v226
	v_bfi_b32 v230, v235, v230, v226
	ds_read2_b32 v[66:67], v253 offset0:39 offset1:38
	ds_read2_b32 v[68:69], v253 offset0:37 offset1:36
	ds_read2_b32 v[70:71], v253 offset0:35 offset1:34
	ds_read2_b32 v[72:73], v253 offset0:33 offset1:32
	ds_read2_b32 v[74:75], v253 offset0:7 offset1:6
	ds_read2_b32 v[76:77], v253 offset0:5 offset1:4
	ds_read2_b32 v[78:79], v253 offset0:3 offset1:2
	ds_read2_b32 v[80:81], v253 offset0:1 offset1:0
	ds_read2_b32 v[236:237], v230 offset0:39 offset1:38
	ds_read2_b32 v[238:239], v230 offset0:37 offset1:36
	ds_read2_b32 v[240:241], v230 offset0:35 offset1:34
	ds_read2_b32 v[242:243], v230 offset0:33 offset1:32
	ds_read_b128 v[50:53], v170 offset:0
	ds_read_b128 v[54:57], v171 offset:0
	s_waitcnt lgkmcnt(0)
	ds_read_b128 v[58:61], v170 offset:512
	ds_read_b128 v[62:65], v171 offset:512
	ds_read2_b32 v[244:245], v230 offset0:7 offset1:6
	ds_read2_b32 v[246:247], v230 offset0:5 offset1:4
	ds_read2_b32 v[248:249], v230 offset0:3 offset1:2
	ds_read2_b32 v[250:251], v230 offset0:1 offset1:0
	v_mfma_f32_16x16x32_bf16 v[66:69], v[50:53], v[34:37], v[66:69]
	v_mfma_f32_16x16x32_bf16 v[66:69], v[54:57], v[38:41], v[66:69]
	v_mfma_f32_16x16x32_bf16 v[236:239], v[50:53], v[42:45], v[236:239]
	v_mfma_f32_16x16x32_bf16 v[236:239], v[54:57], v[46:49], v[236:239]
	ds_read_b128 v[50:53], v170 offset:4096
	ds_read_b128 v[54:57], v171 offset:4096
	s_waitcnt lgkmcnt(6)
	v_mfma_f32_16x16x32_bf16 v[70:73], v[58:61], v[34:37], v[70:73]
	v_mfma_f32_16x16x32_bf16 v[70:73], v[62:65], v[38:41], v[70:73]
	v_mfma_f32_16x16x32_bf16 v[240:243], v[58:61], v[42:45], v[240:243]
	v_mfma_f32_16x16x32_bf16 v[240:243], v[62:65], v[46:49], v[240:243]
	ds_read_b128 v[58:61], v170 offset:4608
	ds_read_b128 v[62:65], v171 offset:4608
	s_waitcnt lgkmcnt(2)
	v_mfma_f32_16x16x32_bf16 v[74:77], v[50:53], v[34:37], v[74:77]
	v_mfma_f32_16x16x32_bf16 v[74:77], v[54:57], v[38:41], v[74:77]
	v_mfma_f32_16x16x32_bf16 v[244:247], v[50:53], v[42:45], v[244:247]
	v_mfma_f32_16x16x32_bf16 v[244:247], v[54:57], v[46:49], v[244:247]
	s_waitcnt lgkmcnt(0)
	v_mfma_f32_16x16x32_bf16 v[78:81], v[58:61], v[34:37], v[78:81]
	v_mfma_f32_16x16x32_bf16 v[78:81], v[62:65], v[38:41], v[78:81]
	v_mfma_f32_16x16x32_bf16 v[248:251], v[58:61], v[42:45], v[248:251]
	v_mfma_f32_16x16x32_bf16 v[248:251], v[62:65], v[46:49], v[248:251]
	s_branch .Lnsa_psm_17
.Lnsa_pfar_16:
	ds_read_b128 v[50:53], v170 offset:0
	ds_read_b128 v[54:57], v171 offset:0
	ds_read_b128 v[58:61], v170 offset:512
	ds_read_b128 v[62:65], v171 offset:512
	v_bfi_b32 v216, v234, v225, v252
	v_bfi_b32 v220, v235, v225, v252
	v_mov_b32_e32 v217, v216
	v_mov_b32_e32 v218, v216
	v_mov_b32_e32 v219, v216
	v_mov_b32_e32 v221, v220
	v_mov_b32_e32 v222, v220
	v_mov_b32_e32 v223, v220
	s_waitcnt lgkmcnt(2)
	v_mfma_f32_16x16x32_bf16 v[66:69], v[50:53], v[34:37], v[216:219]
	v_mfma_f32_16x16x32_bf16 v[236:239], v[50:53], v[42:45], v[220:223]
	v_mfma_f32_16x16x32_bf16 v[66:69], v[54:57], v[38:41], v[66:69]
	v_mfma_f32_16x16x32_bf16 v[236:239], v[54:57], v[46:49], v[236:239]
	ds_read_b128 v[50:53], v170 offset:4096
	ds_read_b128 v[54:57], v171 offset:4096
	s_waitcnt lgkmcnt(2)
	v_mfma_f32_16x16x32_bf16 v[70:73], v[58:61], v[34:37], v[216:219]
	v_mfma_f32_16x16x32_bf16 v[240:243], v[58:61], v[42:45], v[220:223]
	v_mfma_f32_16x16x32_bf16 v[70:73], v[62:65], v[38:41], v[70:73]
	v_mfma_f32_16x16x32_bf16 v[240:243], v[62:65], v[46:49], v[240:243]
	ds_read_b128 v[58:61], v170 offset:4608
	ds_read_b128 v[62:65], v171 offset:4608
	s_waitcnt lgkmcnt(2)
	v_mfma_f32_16x16x32_bf16 v[74:77], v[50:53], v[34:37], v[216:219]
	v_mfma_f32_16x16x32_bf16 v[244:247], v[50:53], v[42:45], v[220:223]
	v_mfma_f32_16x16x32_bf16 v[74:77], v[54:57], v[38:41], v[74:77]
	v_mfma_f32_16x16x32_bf16 v[244:247], v[54:57], v[46:49], v[244:247]
	s_waitcnt lgkmcnt(0)
	v_mfma_f32_16x16x32_bf16 v[78:81], v[58:61], v[34:37], v[216:219]
	v_mfma_f32_16x16x32_bf16 v[248:251], v[58:61], v[42:45], v[220:223]
	v_mfma_f32_16x16x32_bf16 v[78:81], v[62:65], v[38:41], v[78:81]
	v_mfma_f32_16x16x32_bf16 v[248:251], v[62:65], v[46:49], v[248:251]
; #define LAS __attribute__((address_space(3)))
; #define CBAR() asm volatile("" ::: "memory")
; #define MFMA16(a, b, c) __builtin_amdgcn_mfma_f32_16x16x32_bf16(a, b, c, 0, 0, 0)
; __device__ __forceinline__ bf16_t tobf(float x) { return (bf16_t)pk2(x, 0.f); }
; __device__ __forceinline__ float ex2(float x) { return __builtin_amdgcn_exp2f(x); }
; template <int MODE> ...
;     ...
;                 if (far) {
; #pragma unroll
;                     for (int cc = 0; cc < 4; ++cc)
; #pragma unroll
;                         for (int i = 0; i < 4; ++i) { const float p = mb[i] ? ex2(sc[cc][i] + bfar) : 0.f; ls[tile][i] += p; Pb[(4 * q4 + i) * 72 + cc * 16 + r16] = tobf(p); }
;                 } else {
; #pragma unroll
;                     for (int cc = 0; cc < 4; ++cc) { const int pos = j * 64 + cc * 16 + r16;
; #pragma unroll
;                         for (int i = 0; i < 4; ++i) { const int dist = t0 + i - pos; const bool ok = MODE ? ((unsigned)dist < 512u) : (dist >= 0 && mb[i]);
;                             const float p = ok ? ex2(sc[cc][i] + bt[clampd(dist)]) : 0.f; ls[tile][i] += p; Pb[(4 * q4 + i) * 72 + cc * 16 + r16] = tobf(p); } }
;                 }
;                 CBAR();
; #pragma unroll
;                 for (int ks = 0; ks < 2; ++ks) { const bf16x8 aP = *(const LAS bf16x8*)(Pb + r16 * 72 + ks * 32 + q4 * 8);
; #pragma unroll
;                     for (int nt = 0; nt < 4; ++nt) os[tile][nt] = MFMA16(aP, *(const LAS bf16x8*)(Vs + (nt * 16 + r16) * 72 + ks * 32 + q4 * 8), os[tile][nt]); }
;                 CBAR();
.Lnsa_psm_17:
	s_waitcnt lgkmcnt(0)
	v_exp_f32_e32 v66, v66
	v_exp_f32_e32 v67, v67
	v_exp_f32_e32 v68, v68
	v_exp_f32_e32 v69, v69
	v_exp_f32_e32 v70, v70
	v_exp_f32_e32 v71, v71
	v_exp_f32_e32 v72, v72
	v_exp_f32_e32 v73, v73
	v_exp_f32_e32 v74, v74
	v_exp_f32_e32 v75, v75
	v_exp_f32_e32 v76, v76
	v_exp_f32_e32 v77, v77
	v_exp_f32_e32 v78, v78
	v_exp_f32_e32 v79, v79
	v_exp_f32_e32 v80, v80
	v_exp_f32_e32 v81, v81
	v_exp_f32_e32 v236, v236
	v_exp_f32_e32 v237, v237
	v_exp_f32_e32 v238, v238
	v_exp_f32_e32 v239, v239
	v_exp_f32_e32 v240, v240
	v_exp_f32_e32 v241, v241
	v_exp_f32_e32 v242, v242
	v_exp_f32_e32 v243, v243
	v_exp_f32_e32 v244, v244
	v_exp_f32_e32 v245, v245
	v_exp_f32_e32 v246, v246
	v_exp_f32_e32 v247, v247
	v_exp_f32_e32 v248, v248
	v_exp_f32_e32 v249, v249
	v_exp_f32_e32 v250, v250
	v_exp_f32_e32 v251, v251
	v_cvt_pk_bf16_f32 v82, v66, v67
	v_cvt_pk_bf16_f32 v83, v68, v69
	v_cvt_pk_bf16_f32 v84, v70, v71
	v_cvt_pk_bf16_f32 v85, v72, v73
	v_cvt_pk_bf16_f32 v86, v74, v75
	v_cvt_pk_bf16_f32 v87, v76, v77
	v_cvt_pk_bf16_f32 v88, v78, v79
	v_cvt_pk_bf16_f32 v89, v80, v81
	v_add_f32_e32 v66, v66, v67
	v_add_f32_e32 v68, v68, v69
	v_add_f32_e32 v70, v70, v71
	v_add_f32_e32 v72, v72, v73
	v_add_f32_e32 v74, v74, v75
	v_add_f32_e32 v76, v76, v77
	v_add_f32_e32 v78, v78, v79
	v_add_f32_e32 v80, v80, v81
	v_add_f32_e32 v66, v66, v68
	v_add_f32_e32 v70, v70, v72
	v_add_f32_e32 v74, v74, v76
	v_add_f32_e32 v78, v78, v80
	v_add_f32_e32 v66, v66, v70
	v_add_f32_e32 v74, v74, v78
	v_add_f32_e32 v66, v66, v74
	v_add_f32_e32 v215, v215, v66
	v_cvt_pk_bf16_f32 v90, v236, v237
	v_cvt_pk_bf16_f32 v91, v238, v239
	v_cvt_pk_bf16_f32 v92, v240, v241
	v_cvt_pk_bf16_f32 v93, v242, v243
	v_cvt_pk_bf16_f32 v94, v244, v245
	v_cvt_pk_bf16_f32 v95, v246, v247
	v_cvt_pk_bf16_f32 v96, v248, v249
	v_cvt_pk_bf16_f32 v97, v250, v251
	v_add_f32_e32 v236, v236, v237
	v_add_f32_e32 v238, v238, v239
	v_add_f32_e32 v240, v240, v241
	v_add_f32_e32 v242, v242, v243
	v_add_f32_e32 v244, v244, v245
	v_add_f32_e32 v246, v246, v247
	v_add_f32_e32 v248, v248, v249
	v_add_f32_e32 v250, v250, v251
	v_add_f32_e32 v236, v236, v238
	v_add_f32_e32 v240, v240, v242
	v_add_f32_e32 v244, v244, v246
	v_add_f32_e32 v248, v248, v250
	v_add_f32_e32 v236, v236, v240
	v_add_f32_e32 v244, v244, v248
	v_add_f32_e32 v236, v236, v244
	v_add_f32_e32 v224, v224, v236
	s_branch .Lnsa_blkend_15
.Lnsa_nopair_13:
	s_bitcmp1_b32 s34, 0
	s_cbranch_scc0 .Lnsa_single1_14
	s_cmp_eq_u32 s42, 1
	s_cbranch_scc1 .Lnsa_gen_18
	s_cmp_eq_u32 s42, 2
	s_cbranch_scc1 .Lnsa_far_19
	v_bfi_b32 v230, v234, v231, v226
	ds_read2_b32 v[66:67], v230 offset0:39 offset1:38
	ds_read2_b32 v[68:69], v230 offset0:37 offset1:36
	ds_read2_b32 v[70:71], v230 offset0:35 offset1:34
	ds_read2_b32 v[72:73], v230 offset0:33 offset1:32
	ds_read2_b32 v[74:75], v230 offset0:7 offset1:6
	ds_read2_b32 v[76:77], v230 offset0:5 offset1:4
	ds_read2_b32 v[78:79], v230 offset0:3 offset1:2
	ds_read2_b32 v[80:81], v230 offset0:1 offset1:0
	ds_read_b128 v[50:53], v170 offset:0
	ds_read_b128 v[54:57], v171 offset:0
	ds_read_b128 v[58:61], v170 offset:512
	ds_read_b128 v[62:65], v171 offset:512
	s_waitcnt lgkmcnt(2)
	v_mfma_f32_16x16x32_bf16 v[66:69], v[50:53], v[34:37], v[66:69]
	v_mfma_f32_16x16x32_bf16 v[66:69], v[54:57], v[38:41], v[66:69]
	ds_read_b128 v[50:53], v170 offset:4096
	ds_read_b128 v[54:57], v171 offset:4096
	s_waitcnt lgkmcnt(2)
	v_mfma_f32_16x16x32_bf16 v[70:73], v[58:61], v[34:37], v[70:73]
	v_mfma_f32_16x16x32_bf16 v[70:73], v[62:65], v[38:41], v[70:73]
	ds_read_b128 v[58:61], v170 offset:4608
	ds_read_b128 v[62:65], v171 offset:4608
	s_waitcnt lgkmcnt(2)
	v_mfma_f32_16x16x32_bf16 v[74:77], v[50:53], v[34:37], v[74:77]
	v_mfma_f32_16x16x32_bf16 v[74:77], v[54:57], v[38:41], v[74:77]
	s_waitcnt lgkmcnt(0)
	v_mfma_f32_16x16x32_bf16 v[78:81], v[58:61], v[34:37], v[78:81]
	v_mfma_f32_16x16x32_bf16 v[78:81], v[62:65], v[38:41], v[78:81]
	s_branch .Lnsa_ssm_20
.Lnsa_far_19:
	v_bfi_b32 v216, v234, v225, v252
	v_mov_b32_e32 v217, v216
	v_mov_b32_e32 v218, v216
	v_mov_b32_e32 v219, v216
	ds_read_b128 v[50:53], v170 offset:0
	ds_read_b128 v[54:57], v171 offset:0
	ds_read_b128 v[58:61], v170 offset:512
	ds_read_b128 v[62:65], v171 offset:512
	s_waitcnt lgkmcnt(2)
	v_mfma_f32_16x16x32_bf16 v[66:69], v[50:53], v[34:37], v[216:219]
	v_mfma_f32_16x16x32_bf16 v[66:69], v[54:57], v[38:41], v[66:69]
	ds_read_b128 v[50:53], v170 offset:4096
	ds_read_b128 v[54:57], v171 offset:4096
	s_waitcnt lgkmcnt(2)
	v_mfma_f32_16x16x32_bf16 v[70:73], v[58:61], v[34:37], v[216:219]
	v_mfma_f32_16x16x32_bf16 v[70:73], v[62:65], v[38:41], v[70:73]
	ds_read_b128 v[58:61], v170 offset:4608
	ds_read_b128 v[62:65], v171 offset:4608
	s_waitcnt lgkmcnt(2)
	v_mfma_f32_16x16x32_bf16 v[74:77], v[50:53], v[34:37], v[216:219]
	v_mfma_f32_16x16x32_bf16 v[74:77], v[54:57], v[38:41], v[74:77]
	s_waitcnt lgkmcnt(0)
	v_mfma_f32_16x16x32_bf16 v[78:81], v[58:61], v[34:37], v[216:219]
	v_mfma_f32_16x16x32_bf16 v[78:81], v[62:65], v[38:41], v[78:81]
	s_branch .Lnsa_ssm_20
; __device__ __forceinline__ bf16_t tobf(float x) { return (bf16_t)pk2(x, 0.f); }
; __device__ __forceinline__ float ex2(float x) { return __builtin_amdgcn_exp2f(x); }
; template <int MODE> ...
;     ...
; #pragma unroll
;                     for (int cc = 0; cc < 4; ++cc) { const int pos = j * 64 + cc * 16 + r16;
; #pragma unroll
;                         for (int i = 0; i < 4; ++i) { const int dist = t0 + i - pos; const bool ok = MODE ? ((unsigned)dist < 512u) : (dist >= 0 && mb[i]);
;                             const float p = ok ? ex2(sc[cc][i] + bt[clampd(dist)]) : 0.f; ls[tile][i] += p; Pb[(4 * q4 + i) * 72 + cc * 16 + r16] = tobf(p); } }
.Lnsa_gen_18:
	v_bfi_b32 v216, v234, v1, v252
	v_mov_b32_e32 v217, v216
	v_mov_b32_e32 v218, v216
	v_mov_b32_e32 v219, v216
	v_mov_b32_e32 v227, v229
	ds_read_b128 v[50:53], v170 offset:0
	ds_read_b128 v[54:57], v171 offset:0
	ds_read_b128 v[58:61], v170 offset:512
	ds_read_b128 v[62:65], v171 offset:512
	s_waitcnt lgkmcnt(2)
	v_mfma_f32_16x16x32_bf16 v[66:69], v[50:53], v[34:37], v[216:219]
	v_mfma_f32_16x16x32_bf16 v[66:69], v[54:57], v[38:41], v[66:69]
	ds_read_b128 v[50:53], v170 offset:4096
	ds_read_b128 v[54:57], v171 offset:4096
	s_waitcnt lgkmcnt(2)
	v_mfma_f32_16x16x32_bf16 v[70:73], v[58:61], v[34:37], v[216:219]
	v_mfma_f32_16x16x32_bf16 v[70:73], v[62:65], v[38:41], v[70:73]
	ds_read_b128 v[58:61], v170 offset:4608
	ds_read_b128 v[62:65], v171 offset:4608
	s_waitcnt lgkmcnt(2)
	v_mfma_f32_16x16x32_bf16 v[74:77], v[50:53], v[34:37], v[216:219]
	v_mfma_f32_16x16x32_bf16 v[74:77], v[54:57], v[38:41], v[74:77]
	s_waitcnt lgkmcnt(0)
	v_mfma_f32_16x16x32_bf16 v[78:81], v[58:61], v[34:37], v[216:219]
	v_mfma_f32_16x16x32_bf16 v[78:81], v[62:65], v[38:41], v[78:81]
	v_bfe_u32 v253, v184, 2, 2
	v_mul_u32_u24_e32 v253, 0x1010, v253
	v_add_u32_e32 v230, 0x0, v227
	v_min_u32_e32 v230, 0x400, v230
	v_lshl_add_u32 v230, v230, 2, v253
	ds_read_b32 v50, v230
	v_add_u32_e32 v230, 0xffffffff, v227
	v_min_u32_e32 v230, 0x400, v230
	v_lshl_add_u32 v230, v230, 2, v253
	ds_read_b32 v51, v230
	v_add_u32_e32 v230, 0xfffffffe, v227
	v_min_u32_e32 v230, 0x400, v230
	v_lshl_add_u32 v230, v230, 2, v253
	ds_read_b32 v52, v230
	v_add_u32_e32 v230, 0xfffffffd, v227
	v_min_u32_e32 v230, 0x400, v230
	v_lshl_add_u32 v230, v230, 2, v253
	ds_read_b32 v53, v230
	v_add_u32_e32 v230, 0xfffffffc, v227
	v_min_u32_e32 v230, 0x400, v230
	v_lshl_add_u32 v230, v230, 2, v253
	ds_read_b32 v54, v230
	v_add_u32_e32 v230, 0xfffffffb, v227
	v_min_u32_e32 v230, 0x400, v230
	v_lshl_add_u32 v230, v230, 2, v253
	ds_read_b32 v55, v230
	v_add_u32_e32 v230, 0xfffffffa, v227
	v_min_u32_e32 v230, 0x400, v230
	v_lshl_add_u32 v230, v230, 2, v253
	ds_read_b32 v56, v230
	v_add_u32_e32 v230, 0xfffffff9, v227
	v_min_u32_e32 v230, 0x400, v230
	v_lshl_add_u32 v230, v230, 2, v253
	ds_read_b32 v57, v230
	s_waitcnt lgkmcnt(7)
	v_add_u32_e32 v230, 0x0, v227
	v_cmp_gt_u32_e32 vcc, s52, v230
	s_nop 1
	v_cndmask_b32_e32 v50, v252, v50, vcc
	v_add_f32_e32 v66, v66, v50
	s_waitcnt lgkmcnt(6)
	v_add_u32_e32 v230, 0xffffffff, v227
	v_cmp_gt_u32_e32 vcc, s52, v230
	s_nop 1
	v_cndmask_b32_e32 v51, v252, v51, vcc
	v_add_f32_e32 v67, v67, v51
	s_waitcnt lgkmcnt(5)
	v_add_u32_e32 v230, 0xfffffffe, v227
	v_cmp_gt_u32_e32 vcc, s52, v230
	s_nop 1
	v_cndmask_b32_e32 v52, v252, v52, vcc
	v_add_f32_e32 v68, v68, v52
	s_waitcnt lgkmcnt(4)
	v_add_u32_e32 v230, 0xfffffffd, v227
	v_cmp_gt_u32_e32 vcc, s52, v230
	s_nop 1
	v_cndmask_b32_e32 v53, v252, v53, vcc
	v_add_f32_e32 v69, v69, v53
	s_waitcnt lgkmcnt(3)
	v_add_u32_e32 v230, 0xfffffffc, v227
	v_cmp_gt_u32_e32 vcc, s52, v230
	s_nop 1
	v_cndmask_b32_e32 v54, v252, v54, vcc
	v_add_f32_e32 v70, v70, v54
	s_waitcnt lgkmcnt(2)
	v_add_u32_e32 v230, 0xfffffffb, v227
	v_cmp_gt_u32_e32 vcc, s52, v230
	s_nop 1
	v_cndmask_b32_e32 v55, v252, v55, vcc
	v_add_f32_e32 v71, v71, v55
	s_waitcnt lgkmcnt(1)
	v_add_u32_e32 v230, 0xfffffffa, v227
	v_cmp_gt_u32_e32 vcc, s52, v230
	s_nop 1
	v_cndmask_b32_e32 v56, v252, v56, vcc
	v_add_f32_e32 v72, v72, v56
	s_waitcnt lgkmcnt(0)
	v_add_u32_e32 v230, 0xfffffff9, v227
	v_cmp_gt_u32_e32 vcc, s52, v230
	s_nop 1
	v_cndmask_b32_e32 v57, v252, v57, vcc
	v_add_f32_e32 v73, v73, v57
	v_add_u32_e32 v230, 0xffffffe0, v227
	v_min_u32_e32 v230, 0x400, v230
	v_lshl_add_u32 v230, v230, 2, v253
	ds_read_b32 v50, v230
	v_add_u32_e32 v230, 0xffffffdf, v227
	v_min_u32_e32 v230, 0x400, v230
	v_lshl_add_u32 v230, v230, 2, v253
	ds_read_b32 v51, v230
	v_add_u32_e32 v230, 0xffffffde, v227
	v_min_u32_e32 v230, 0x400, v230
	v_lshl_add_u32 v230, v230, 2, v253
	ds_read_b32 v52, v230
	v_add_u32_e32 v230, 0xffffffdd, v227
	v_min_u32_e32 v230, 0x400, v230
	v_lshl_add_u32 v230, v230, 2, v253
	ds_read_b32 v53, v230
	v_add_u32_e32 v230, 0xffffffdc, v227
	v_min_u32_e32 v230, 0x400, v230
	v_lshl_add_u32 v230, v230, 2, v253
	ds_read_b32 v54, v230
	v_add_u32_e32 v230, 0xffffffdb, v227
	v_min_u32_e32 v230, 0x400, v230
	v_lshl_add_u32 v230, v230, 2, v253
	ds_read_b32 v55, v230
	v_add_u32_e32 v230, 0xffffffda, v227
	v_min_u32_e32 v230, 0x400, v230
	v_lshl_add_u32 v230, v230, 2, v253
	ds_read_b32 v56, v230
	v_add_u32_e32 v230, 0xffffffd9, v227
	v_min_u32_e32 v230, 0x400, v230
	v_lshl_add_u32 v230, v230, 2, v253
	ds_read_b32 v57, v230
	s_waitcnt lgkmcnt(7)
	v_add_u32_e32 v230, 0xffffffe0, v227
	v_cmp_gt_u32_e32 vcc, s52, v230
	s_nop 1
	v_cndmask_b32_e32 v50, v252, v50, vcc
	v_add_f32_e32 v74, v74, v50
	s_waitcnt lgkmcnt(6)
	v_add_u32_e32 v230, 0xffffffdf, v227
	v_cmp_gt_u32_e32 vcc, s52, v230
	s_nop 1
	v_cndmask_b32_e32 v51, v252, v51, vcc
	v_add_f32_e32 v75, v75, v51
	s_waitcnt lgkmcnt(5)
	v_add_u32_e32 v230, 0xffffffde, v227
	v_cmp_gt_u32_e32 vcc, s52, v230
	s_nop 1
	v_cndmask_b32_e32 v52, v252, v52, vcc
	v_add_f32_e32 v76, v76, v52
	s_waitcnt lgkmcnt(4)
	v_add_u32_e32 v230, 0xffffffdd, v227
	v_cmp_gt_u32_e32 vcc, s52, v230
	s_nop 1
	v_cndmask_b32_e32 v53, v252, v53, vcc
	v_add_f32_e32 v77, v77, v53
	s_waitcnt lgkmcnt(3)
	v_add_u32_e32 v230, 0xffffffdc, v227
	v_cmp_gt_u32_e32 vcc, s52, v230
	s_nop 1
	v_cndmask_b32_e32 v54, v252, v54, vcc
	v_add_f32_e32 v78, v78, v54
	s_waitcnt lgkmcnt(2)
	v_add_u32_e32 v230, 0xffffffdb, v227
	v_cmp_gt_u32_e32 vcc, s52, v230
	s_nop 1
	v_cndmask_b32_e32 v55, v252, v55, vcc
	v_add_f32_e32 v79, v79, v55
	s_waitcnt lgkmcnt(1)
	v_add_u32_e32 v230, 0xffffffda, v227
	v_cmp_gt_u32_e32 vcc, s52, v230
	s_nop 1
	v_cndmask_b32_e32 v56, v252, v56, vcc
	v_add_f32_e32 v80, v80, v56
	s_waitcnt lgkmcnt(0)
	v_add_u32_e32 v230, 0xffffffd9, v227
	v_cmp_gt_u32_e32 vcc, s52, v230
	s_nop 1
	v_cndmask_b32_e32 v57, v252, v57, vcc
	v_add_f32_e32 v81, v81, v57
; __device__ __forceinline__ bf16_t tobf(float x) { return (bf16_t)pk2(x, 0.f); }
; __device__ __forceinline__ float ex2(float x) { return __builtin_amdgcn_exp2f(x); }
; template <int MODE> ...
;     ...
;                 if (far) {
; #pragma unroll
;                     for (int cc = 0; cc < 4; ++cc)
; #pragma unroll
;                         for (int i = 0; i < 4; ++i) { const float p = mb[i] ? ex2(sc[cc][i] + bfar) : 0.f; ls[tile][i] += p; Pb[(4 * q4 + i) * 72 + cc * 16 + r16] = tobf(p); }
;                 } else {
; #pragma unroll
;                     for (int cc = 0; cc < 4; ++cc) { const int pos = j * 64 + cc * 16 + r16;
; #pragma unroll
;                         for (int i = 0; i < 4; ++i) { const int dist = t0 + i - pos; const bool ok = MODE ? ((unsigned)dist < 512u) : (dist >= 0 && mb[i]);
;                             const float p = ok ? ex2(sc[cc][i] + bt[clampd(dist)]) : 0.f; ls[tile][i] += p; Pb[(4 * q4 + i) * 72 + cc * 16 + r16] = tobf(p); } }
;                 }
.Lnsa_ssm_20:
	s_waitcnt lgkmcnt(0)
	v_exp_f32_e32 v66, v66
	v_exp_f32_e32 v67, v67
	v_exp_f32_e32 v68, v68
	v_exp_f32_e32 v69, v69
	v_exp_f32_e32 v70, v70
	v_exp_f32_e32 v71, v71
	v_exp_f32_e32 v72, v72
	v_exp_f32_e32 v73, v73
	v_exp_f32_e32 v74, v74
	v_exp_f32_e32 v75, v75
	v_exp_f32_e32 v76, v76
	v_exp_f32_e32 v77, v77
	v_exp_f32_e32 v78, v78
	v_exp_f32_e32 v79, v79
	v_exp_f32_e32 v80, v80
	v_exp_f32_e32 v81, v81
	v_cvt_pk_bf16_f32 v82, v66, v67
	v_cvt_pk_bf16_f32 v83, v68, v69
	v_cvt_pk_bf16_f32 v84, v70, v71
	v_cvt_pk_bf16_f32 v85, v72, v73
	v_cvt_pk_bf16_f32 v86, v74, v75
	v_cvt_pk_bf16_f32 v87, v76, v77
	v_cvt_pk_bf16_f32 v88, v78, v79
	v_cvt_pk_bf16_f32 v89, v80, v81
	v_add_f32_e32 v66, v66, v67
	v_add_f32_e32 v68, v68, v69
	v_add_f32_e32 v70, v70, v71
	v_add_f32_e32 v72, v72, v73
	v_add_f32_e32 v74, v74, v75
	v_add_f32_e32 v76, v76, v77
	v_add_f32_e32 v78, v78, v79
	v_add_f32_e32 v80, v80, v81
	v_add_f32_e32 v66, v66, v68
	v_add_f32_e32 v70, v70, v72
	v_add_f32_e32 v74, v74, v76
	v_add_f32_e32 v78, v78, v80
	v_add_f32_e32 v66, v66, v70
	v_add_f32_e32 v74, v74, v78
	v_add_f32_e32 v66, v66, v74
	v_add_f32_e32 v215, v215, v66
.Lnsa_single1_14:
	s_bitcmp1_b32 s34, 1
	s_cbranch_scc0 .Lnsa_blkend_15
	s_cmp_eq_u32 s42, 1
	s_cbranch_scc1 .Lnsa_gen_21
	s_cmp_eq_u32 s42, 2
	s_cbranch_scc1 .Lnsa_far_22
	v_add_u32_e32 v230, 16, v231
	v_bfi_b32 v230, v235, v230, v226
	ds_read2_b32 v[66:67], v230 offset0:39 offset1:38
	ds_read2_b32 v[68:69], v230 offset0:37 offset1:36
	ds_read2_b32 v[70:71], v230 offset0:35 offset1:34
	ds_read2_b32 v[72:73], v230 offset0:33 offset1:32
	ds_read2_b32 v[74:75], v230 offset0:7 offset1:6
	ds_read2_b32 v[76:77], v230 offset0:5 offset1:4
	ds_read2_b32 v[78:79], v230 offset0:3 offset1:2
	ds_read2_b32 v[80:81], v230 offset0:1 offset1:0
	ds_read_b128 v[50:53], v170 offset:0
	ds_read_b128 v[54:57], v171 offset:0
	ds_read_b128 v[58:61], v170 offset:512
	ds_read_b128 v[62:65], v171 offset:512
	s_waitcnt lgkmcnt(2)
	v_mfma_f32_16x16x32_bf16 v[66:69], v[50:53], v[42:45], v[66:69]
	v_mfma_f32_16x16x32_bf16 v[66:69], v[54:57], v[46:49], v[66:69]
	ds_read_b128 v[50:53], v170 offset:4096
	ds_read_b128 v[54:57], v171 offset:4096
	s_waitcnt lgkmcnt(2)
	v_mfma_f32_16x16x32_bf16 v[70:73], v[58:61], v[42:45], v[70:73]
	v_mfma_f32_16x16x32_bf16 v[70:73], v[62:65], v[46:49], v[70:73]
	ds_read_b128 v[58:61], v170 offset:4608
	ds_read_b128 v[62:65], v171 offset:4608
	s_waitcnt lgkmcnt(2)
	v_mfma_f32_16x16x32_bf16 v[74:77], v[50:53], v[42:45], v[74:77]
	v_mfma_f32_16x16x32_bf16 v[74:77], v[54:57], v[46:49], v[74:77]
	s_waitcnt lgkmcnt(0)
	v_mfma_f32_16x16x32_bf16 v[78:81], v[58:61], v[42:45], v[78:81]
	v_mfma_f32_16x16x32_bf16 v[78:81], v[62:65], v[46:49], v[78:81]
	s_branch .Lnsa_ssm_23
.Lnsa_far_22:
	v_bfi_b32 v216, v235, v225, v252
	v_mov_b32_e32 v217, v216
	v_mov_b32_e32 v218, v216
	v_mov_b32_e32 v219, v216
	ds_read_b128 v[50:53], v170 offset:0
	ds_read_b128 v[54:57], v171 offset:0
	ds_read_b128 v[58:61], v170 offset:512
	ds_read_b128 v[62:65], v171 offset:512
	s_waitcnt lgkmcnt(2)
	v_mfma_f32_16x16x32_bf16 v[66:69], v[50:53], v[42:45], v[216:219]
	v_mfma_f32_16x16x32_bf16 v[66:69], v[54:57], v[46:49], v[66:69]
	ds_read_b128 v[50:53], v170 offset:4096
	ds_read_b128 v[54:57], v171 offset:4096
	s_waitcnt lgkmcnt(2)
	v_mfma_f32_16x16x32_bf16 v[70:73], v[58:61], v[42:45], v[216:219]
	v_mfma_f32_16x16x32_bf16 v[70:73], v[62:65], v[46:49], v[70:73]
	ds_read_b128 v[58:61], v170 offset:4608
	ds_read_b128 v[62:65], v171 offset:4608
	s_waitcnt lgkmcnt(2)
	v_mfma_f32_16x16x32_bf16 v[74:77], v[50:53], v[42:45], v[216:219]
	v_mfma_f32_16x16x32_bf16 v[74:77], v[54:57], v[46:49], v[74:77]
	s_waitcnt lgkmcnt(0)
	v_mfma_f32_16x16x32_bf16 v[78:81], v[58:61], v[42:45], v[216:219]
	v_mfma_f32_16x16x32_bf16 v[78:81], v[62:65], v[46:49], v[78:81]
	s_branch .Lnsa_ssm_23
.Lnsa_gen_21:
	v_bfi_b32 v216, v235, v1, v252
	v_mov_b32_e32 v217, v216
	v_mov_b32_e32 v218, v216
	v_mov_b32_e32 v219, v216
	v_add_u32_e32 v227, 4, v229
	ds_read_b128 v[50:53], v170 offset:0
	ds_read_b128 v[54:57], v171 offset:0
	ds_read_b128 v[58:61], v170 offset:512
	ds_read_b128 v[62:65], v171 offset:512
	s_waitcnt lgkmcnt(2)
	v_mfma_f32_16x16x32_bf16 v[66:69], v[50:53], v[42:45], v[216:219]
	v_mfma_f32_16x16x32_bf16 v[66:69], v[54:57], v[46:49], v[66:69]
	ds_read_b128 v[50:53], v170 offset:4096
	ds_read_b128 v[54:57], v171 offset:4096
	s_waitcnt lgkmcnt(2)
	v_mfma_f32_16x16x32_bf16 v[70:73], v[58:61], v[42:45], v[216:219]
	v_mfma_f32_16x16x32_bf16 v[70:73], v[62:65], v[46:49], v[70:73]
	ds_read_b128 v[58:61], v170 offset:4608
	ds_read_b128 v[62:65], v171 offset:4608
	s_waitcnt lgkmcnt(2)
	v_mfma_f32_16x16x32_bf16 v[74:77], v[50:53], v[42:45], v[216:219]
	v_mfma_f32_16x16x32_bf16 v[74:77], v[54:57], v[46:49], v[74:77]
	s_waitcnt lgkmcnt(0)
	v_mfma_f32_16x16x32_bf16 v[78:81], v[58:61], v[42:45], v[216:219]
	v_mfma_f32_16x16x32_bf16 v[78:81], v[62:65], v[46:49], v[78:81]
	v_bfe_u32 v253, v184, 2, 2
	v_mul_u32_u24_e32 v253, 0x1010, v253
	v_add_u32_e32 v230, 0x0, v227
	v_min_u32_e32 v230, 0x400, v230
	v_lshl_add_u32 v230, v230, 2, v253
	ds_read_b32 v50, v230
	v_add_u32_e32 v230, 0xffffffff, v227
	v_min_u32_e32 v230, 0x400, v230
	v_lshl_add_u32 v230, v230, 2, v253
	ds_read_b32 v51, v230
	v_add_u32_e32 v230, 0xfffffffe, v227
	v_min_u32_e32 v230, 0x400, v230
	v_lshl_add_u32 v230, v230, 2, v253
	ds_read_b32 v52, v230
	v_add_u32_e32 v230, 0xfffffffd, v227
	v_min_u32_e32 v230, 0x400, v230
	v_lshl_add_u32 v230, v230, 2, v253
	ds_read_b32 v53, v230
	v_add_u32_e32 v230, 0xfffffffc, v227
	v_min_u32_e32 v230, 0x400, v230
	v_lshl_add_u32 v230, v230, 2, v253
	ds_read_b32 v54, v230
	v_add_u32_e32 v230, 0xfffffffb, v227
	v_min_u32_e32 v230, 0x400, v230
	v_lshl_add_u32 v230, v230, 2, v253
	ds_read_b32 v55, v230
	v_add_u32_e32 v230, 0xfffffffa, v227
	v_min_u32_e32 v230, 0x400, v230
	v_lshl_add_u32 v230, v230, 2, v253
	ds_read_b32 v56, v230
	v_add_u32_e32 v230, 0xfffffff9, v227
	v_min_u32_e32 v230, 0x400, v230
	v_lshl_add_u32 v230, v230, 2, v253
	ds_read_b32 v57, v230
	s_waitcnt lgkmcnt(7)
; #define LAS __attribute__((address_space(3)))
; #define CBAR() asm volatile("" ::: "memory")
; #define MFMA16(a, b, c) __builtin_amdgcn_mfma_f32_16x16x32_bf16(a, b, c, 0, 0, 0)
; __device__ __forceinline__ bf16_t tobf(float x) { return (bf16_t)pk2(x, 0.f); }
; __device__ __forceinline__ float ex2(float x) { return __builtin_amdgcn_exp2f(x); }
; #define NSA_ST1(st_, half_) do { LAS bf16_t* nx_ = stage + (st_) * 18432 + (half_) * 9216 + soff; *(LAS bf16x8*)nx_ = kr; *(LAS bf16x8*)(nx_ + 4608) = vr; } while (0)
; template <int MODE> ...
;     ...
; #pragma unroll
;                     for (int cc = 0; cc < 4; ++cc) { const int pos = j * 64 + cc * 16 + r16;
; #pragma unroll
;                         for (int i = 0; i < 4; ++i) { const int dist = t0 + i - pos; const bool ok = MODE ? ((unsigned)dist < 512u) : (dist >= 0 && mb[i]);
;                             const float p = ok ? ex2(sc[cc][i] + bt[clampd(dist)]) : 0.f; ls[tile][i] += p; Pb[(4 * q4 + i) * 72 + cc * 16 + r16] = tobf(p); } }
;                 }
;                 CBAR();
; #pragma unroll
;                 for (int ks = 0; ks < 2; ++ks) { const bf16x8 aP = *(const LAS bf16x8*)(Pb + r16 * 72 + ks * 32 + q4 * 8);
; #pragma unroll
;                     for (int nt = 0; nt < 4; ++nt) os[tile][nt] = MFMA16(aP, *(const LAS bf16x8*)(Vs + (nt * 16 + r16) * 72 + ks * 32 + q4 * 8), os[tile][nt]); }
;                 CBAR();
;             }
;         }
;         if (pre) NSA_ST1(pp ^ 1, sub);
;       }
;         __syncthreads();
	v_add_u32_e32 v230, 0x0, v227
	v_cmp_gt_u32_e32 vcc, s52, v230
	s_nop 1
	v_cndmask_b32_e32 v50, v252, v50, vcc
	v_add_f32_e32 v66, v66, v50
	s_waitcnt lgkmcnt(6)
	v_add_u32_e32 v230, 0xffffffff, v227
	v_cmp_gt_u32_e32 vcc, s52, v230
	s_nop 1
	v_cndmask_b32_e32 v51, v252, v51, vcc
	v_add_f32_e32 v67, v67, v51
	s_waitcnt lgkmcnt(5)
	v_add_u32_e32 v230, 0xfffffffe, v227
	v_cmp_gt_u32_e32 vcc, s52, v230
	s_nop 1
	v_cndmask_b32_e32 v52, v252, v52, vcc
	v_add_f32_e32 v68, v68, v52
	s_waitcnt lgkmcnt(4)
	v_add_u32_e32 v230, 0xfffffffd, v227
	v_cmp_gt_u32_e32 vcc, s52, v230
	s_nop 1
	v_cndmask_b32_e32 v53, v252, v53, vcc
	v_add_f32_e32 v69, v69, v53
	s_waitcnt lgkmcnt(3)
	v_add_u32_e32 v230, 0xfffffffc, v227
	v_cmp_gt_u32_e32 vcc, s52, v230
	s_nop 1
	v_cndmask_b32_e32 v54, v252, v54, vcc
	v_add_f32_e32 v70, v70, v54
	s_waitcnt lgkmcnt(2)
	v_add_u32_e32 v230, 0xfffffffb, v227
	v_cmp_gt_u32_e32 vcc, s52, v230
	s_nop 1
	v_cndmask_b32_e32 v55, v252, v55, vcc
	v_add_f32_e32 v71, v71, v55
	s_waitcnt lgkmcnt(1)
	v_add_u32_e32 v230, 0xfffffffa, v227
	v_cmp_gt_u32_e32 vcc, s52, v230
	s_nop 1
	v_cndmask_b32_e32 v56, v252, v56, vcc
	v_add_f32_e32 v72, v72, v56
	s_waitcnt lgkmcnt(0)
	v_add_u32_e32 v230, 0xfffffff9, v227
	v_cmp_gt_u32_e32 vcc, s52, v230
	s_nop 1
	v_cndmask_b32_e32 v57, v252, v57, vcc
	v_add_f32_e32 v73, v73, v57
	v_add_u32_e32 v230, 0xffffffe0, v227
	v_min_u32_e32 v230, 0x400, v230
	v_lshl_add_u32 v230, v230, 2, v253
	ds_read_b32 v50, v230
	v_add_u32_e32 v230, 0xffffffdf, v227
	v_min_u32_e32 v230, 0x400, v230
	v_lshl_add_u32 v230, v230, 2, v253
	ds_read_b32 v51, v230
	v_add_u32_e32 v230, 0xffffffde, v227
	v_min_u32_e32 v230, 0x400, v230
	v_lshl_add_u32 v230, v230, 2, v253
	ds_read_b32 v52, v230
	v_add_u32_e32 v230, 0xffffffdd, v227
	v_min_u32_e32 v230, 0x400, v230
	v_lshl_add_u32 v230, v230, 2, v253
	ds_read_b32 v53, v230
	v_add_u32_e32 v230, 0xffffffdc, v227
	v_min_u32_e32 v230, 0x400, v230
	v_lshl_add_u32 v230, v230, 2, v253
	ds_read_b32 v54, v230
	v_add_u32_e32 v230, 0xffffffdb, v227
	v_min_u32_e32 v230, 0x400, v230
	v_lshl_add_u32 v230, v230, 2, v253
	ds_read_b32 v55, v230
	v_add_u32_e32 v230, 0xffffffda, v227
	v_min_u32_e32 v230, 0x400, v230
	v_lshl_add_u32 v230, v230, 2, v253
	ds_read_b32 v56, v230
	v_add_u32_e32 v230, 0xffffffd9, v227
	v_min_u32_e32 v230, 0x400, v230
	v_lshl_add_u32 v230, v230, 2, v253
	ds_read_b32 v57, v230
	s_waitcnt lgkmcnt(7)
	v_add_u32_e32 v230, 0xffffffe0, v227
	v_cmp_gt_u32_e32 vcc, s52, v230
	s_nop 1
	v_cndmask_b32_e32 v50, v252, v50, vcc
	v_add_f32_e32 v74, v74, v50
	s_waitcnt lgkmcnt(6)
	v_add_u32_e32 v230, 0xffffffdf, v227
	v_cmp_gt_u32_e32 vcc, s52, v230
	s_nop 1
	v_cndmask_b32_e32 v51, v252, v51, vcc
	v_add_f32_e32 v75, v75, v51
	s_waitcnt lgkmcnt(5)
	v_add_u32_e32 v230, 0xffffffde, v227
	v_cmp_gt_u32_e32 vcc, s52, v230
	s_nop 1
	v_cndmask_b32_e32 v52, v252, v52, vcc
	v_add_f32_e32 v76, v76, v52
	s_waitcnt lgkmcnt(4)
	v_add_u32_e32 v230, 0xffffffdd, v227
	v_cmp_gt_u32_e32 vcc, s52, v230
	s_nop 1
	v_cndmask_b32_e32 v53, v252, v53, vcc
	v_add_f32_e32 v77, v77, v53
	s_waitcnt lgkmcnt(3)
	v_add_u32_e32 v230, 0xffffffdc, v227
	v_cmp_gt_u32_e32 vcc, s52, v230
	s_nop 1
	v_cndmask_b32_e32 v54, v252, v54, vcc
	v_add_f32_e32 v78, v78, v54
	s_waitcnt lgkmcnt(2)
	v_add_u32_e32 v230, 0xffffffdb, v227
	v_cmp_gt_u32_e32 vcc, s52, v230
	s_nop 1
	v_cndmask_b32_e32 v55, v252, v55, vcc
	v_add_f32_e32 v79, v79, v55
	s_waitcnt lgkmcnt(1)
	v_add_u32_e32 v230, 0xffffffda, v227
	v_cmp_gt_u32_e32 vcc, s52, v230
	s_nop 1
	v_cndmask_b32_e32 v56, v252, v56, vcc
	v_add_f32_e32 v80, v80, v56
	s_waitcnt lgkmcnt(0)
	v_add_u32_e32 v230, 0xffffffd9, v227
	v_cmp_gt_u32_e32 vcc, s52, v230
	s_nop 1
	v_cndmask_b32_e32 v57, v252, v57, vcc
	v_add_f32_e32 v81, v81, v57
.Lnsa_ssm_23:
	s_waitcnt lgkmcnt(0)
	v_exp_f32_e32 v66, v66
	v_exp_f32_e32 v67, v67
	v_exp_f32_e32 v68, v68
	v_exp_f32_e32 v69, v69
	v_exp_f32_e32 v70, v70
	v_exp_f32_e32 v71, v71
	v_exp_f32_e32 v72, v72
	v_exp_f32_e32 v73, v73
	v_exp_f32_e32 v74, v74
	v_exp_f32_e32 v75, v75
	v_exp_f32_e32 v76, v76
	v_exp_f32_e32 v77, v77
	v_exp_f32_e32 v78, v78
	v_exp_f32_e32 v79, v79
	v_exp_f32_e32 v80, v80
	v_exp_f32_e32 v81, v81
	v_cvt_pk_bf16_f32 v90, v66, v67
	v_cvt_pk_bf16_f32 v91, v68, v69
	v_cvt_pk_bf16_f32 v92, v70, v71
	v_cvt_pk_bf16_f32 v93, v72, v73
	v_cvt_pk_bf16_f32 v94, v74, v75
	v_cvt_pk_bf16_f32 v95, v76, v77
	v_cvt_pk_bf16_f32 v96, v78, v79
	v_cvt_pk_bf16_f32 v97, v80, v81
	v_add_f32_e32 v66, v66, v67
	v_add_f32_e32 v68, v68, v69
	v_add_f32_e32 v70, v70, v71
	v_add_f32_e32 v72, v72, v73
	v_add_f32_e32 v74, v74, v75
	v_add_f32_e32 v76, v76, v77
	v_add_f32_e32 v78, v78, v79
	v_add_f32_e32 v80, v80, v81
	v_add_f32_e32 v66, v66, v68
	v_add_f32_e32 v70, v70, v72
	v_add_f32_e32 v74, v74, v76
	v_add_f32_e32 v78, v78, v80
	v_add_f32_e32 v66, v66, v70
	v_add_f32_e32 v74, v74, v78
	v_add_f32_e32 v66, v66, v74
	v_add_f32_e32 v224, v224, v66
.Lnsa_blkend_15:
	s_waitcnt vmcnt(2) lgkmcnt(0)
	s_barrier
	s_mov_b32 s93, s94
	s_mov_b32 s94, s95
	s_add_i32 s57, s57, 1
	s_cmp_lt_u32 s57, s92
	s_cbranch_scc1 .Lnsa_blk_loop
	s_cmp_eq_u32 s43, 0
	s_cbranch_scc1 .Lnsa_pvnone_24
	ds_read_b128 v[50:53], v172 offset:0
	ds_read_b128 v[54:57], v173 offset:0
	ds_read_b128 v[58:61], v172 offset:2048
	ds_read_b128 v[62:65], v173 offset:2048
	s_cmp_eq_u32 s43, 3
	s_cbranch_scc0 .Lnsa_pvone_25
	s_waitcnt lgkmcnt(2)
	v_mfma_f32_16x16x32_bf16 v[2:5], v[50:53], v[82:85], v[2:5]
	v_mfma_f32_16x16x32_bf16 v[18:21], v[50:53], v[90:93], v[18:21]
	v_mfma_f32_16x16x32_bf16 v[2:5], v[54:57], v[86:89], v[2:5]
	v_mfma_f32_16x16x32_bf16 v[18:21], v[54:57], v[94:97], v[18:21]
	ds_read_b128 v[50:53], v172 offset:4096
	ds_read_b128 v[54:57], v173 offset:4096
	s_waitcnt lgkmcnt(2)
	v_mfma_f32_16x16x32_bf16 v[6:9], v[58:61], v[82:85], v[6:9]
	v_mfma_f32_16x16x32_bf16 v[22:25], v[58:61], v[90:93], v[22:25]
	v_mfma_f32_16x16x32_bf16 v[6:9], v[62:65], v[86:89], v[6:9]
	v_mfma_f32_16x16x32_bf16 v[22:25], v[62:65], v[94:97], v[22:25]
	ds_read_b128 v[58:61], v172 offset:6144
	ds_read_b128 v[62:65], v173 offset:6144
	s_waitcnt lgkmcnt(2)
	v_mfma_f32_16x16x32_bf16 v[10:13], v[50:53], v[82:85], v[10:13]
	v_mfma_f32_16x16x32_bf16 v[26:29], v[50:53], v[90:93], v[26:29]
	v_mfma_f32_16x16x32_bf16 v[10:13], v[54:57], v[86:89], v[10:13]
	v_mfma_f32_16x16x32_bf16 v[26:29], v[54:57], v[94:97], v[26:29]
	s_waitcnt lgkmcnt(0)
	v_mfma_f32_16x16x32_bf16 v[14:17], v[58:61], v[82:85], v[14:17]
	v_mfma_f32_16x16x32_bf16 v[30:33], v[58:61], v[90:93], v[30:33]
	v_mfma_f32_16x16x32_bf16 v[14:17], v[62:65], v[86:89], v[14:17]
	v_mfma_f32_16x16x32_bf16 v[30:33], v[62:65], v[94:97], v[30:33]
	s_branch .Lnsa_pvend_27

; __device__ __forceinline__ bf16_t tobf(float x) { return (bf16_t)pk2(x, 0.f); }
; __device__ __forceinline__ float red16(float v) { v += __shfl_xor(v, 1); v += __shfl_xor(v, 2); v += __shfl_xor(v, 4); v += __shfl_xor(v, 8); return v; }
; template <int MODE> ...
;     ...
; #pragma unroll
;     for (int tile = 0; tile < 2; ++tile) { const int t0 = qb * 64 + wave * 8 + tile * 4;
; #pragma unroll
;         for (int tt = 0; tt < 4; ++tt) { const float gs = GN[(size_t)(b * SEQ + t0 + tt) * 48 + (g * 4 + q4) * 3 + (MODE ? 2 : 1)] / red16(ls[tile][tt]);
;             bf16_t* op = ONSA + (size_t)(b * SEQ + t0 + tt) * 1024 + (g * 4 + q4) * 64 + r16;
; #pragma unroll
;             for (int nt = 0; nt < 4; ++nt) op[nt * 16] = tobf(bflo((unsigned)op[nt * 16]) + gs * os[tile][nt][tt]); } }
.Lnsa_pvend_27:
	s_waitcnt lgkmcnt(0)
.Lnsa_pvnone_24:
	s_waitcnt vmcnt(0)
	s_barrier
.Lnsa_blk_done:
	s_nop 7
	s_nop 7
	v_and_b32_e32 v66, 15, v184
	v_lshrrev_b32_e32 v67, 4, v184
	v_and_b32_e32 v68, 3, v66
	v_lshrrev_b32_e32 v69, 2, v66
	s_lshl_b32 s0, s18, 6
	s_add_i32 s0, s0, s97
	s_add_i32 s0, s0, s80
	v_add_u32_e32 v70, s0, v68
	s_and_b32 s1, s88, 3
	s_lshl_b32 s1, s1, 2
	v_add_u32_e32 v71, s1, v69
	v_lshlrev_b32_e32 v72, 7, v71
	v_lshl_add_u32 v72, v70, 11, v72
	v_lshl_add_u32 v72, v67, 3, v72
	v_add_u32_e32 v73, 0x2000, v72
	v_mul_u32_u24_e32 v74, 0xc0, v70
	v_mul_u32_u24_e32 v75, 12, v71
	s_lshl_b32 s0, s54, 2
	s_add_i32 s0, s0, 4
	v_add3_u32 v74, v74, v75, s0
	s_add_u32 s70, s30, 0x38310000
	s_addc_u32 s71, s31, 0
	s_add_u32 s14, s30, 0xf900000
	s_addc_u32 s15, s31, 0
	global_load_dword v76, v74, s[70:71] offset:0
	global_load_dword v77, v74, s[70:71] offset:768
	global_load_dwordx2 v[50:51], v72, s[14:15] offset:0
	global_load_dwordx2 v[52:53], v72, s[14:15] offset:32
	global_load_dwordx2 v[54:55], v72, s[14:15] offset:64
	global_load_dwordx2 v[56:57], v72, s[14:15] offset:96
	global_load_dwordx2 v[58:59], v73, s[14:15] offset:0
	global_load_dwordx2 v[60:61], v73, s[14:15] offset:32
	global_load_dwordx2 v[62:63], v73, s[14:15] offset:64
	global_load_dwordx2 v[64:65], v73, s[14:15] offset:96
	v_xor_b32_e32 v78, 16, v184
	v_lshlrev_b32_e32 v78, 2, v78
	v_xor_b32_e32 v79, 32, v184
	v_lshlrev_b32_e32 v79, 2, v79
	ds_bpermute_b32 v237, v78, v215
	s_waitcnt lgkmcnt(0)
	v_add_f32_e32 v236, v215, v237
	ds_bpermute_b32 v237, v79, v236
	s_waitcnt lgkmcnt(0)
	v_add_f32_e32 v236, v236, v237
	ds_bpermute_b32 v245, v78, v224
	s_waitcnt lgkmcnt(0)
	v_add_f32_e32 v244, v224, v245
	ds_bpermute_b32 v245, v79, v244
	s_waitcnt lgkmcnt(0)
	v_add_f32_e32 v244, v244, v245
	s_waitcnt vmcnt(9)
	v_div_scale_f32 v237, s[20:21], v236, v236, v76
	v_rcp_f32_e32 v238, v237
	v_div_scale_f32 v239, vcc, v76, v236, v76
	v_fma_f32 v240, -v237, v238, 1.0
	v_fmac_f32_e32 v238, v240, v238
	v_mul_f32_e32 v240, v239, v238
	v_fma_f32 v241, -v237, v240, v239
	v_fmac_f32_e32 v240, v241, v238
	v_fma_f32 v237, -v237, v240, v239
	s_nop 1
	v_div_fmas_f32 v237, v237, v238, v240
	v_div_fixup_f32 v239, v237, v236, v76
	s_waitcnt vmcnt(8)
	v_div_scale_f32 v245, s[20:21], v244, v244, v77
	v_rcp_f32_e32 v246, v245
	v_div_scale_f32 v247, vcc, v77, v244, v77
	v_fma_f32 v248, -v245, v246, 1.0
	v_fmac_f32_e32 v246, v248, v246
	v_mul_f32_e32 v248, v247, v246
	v_fma_f32 v249, -v245, v248, v247
	v_fmac_f32_e32 v248, v249, v246
	v_fma_f32 v245, -v245, v248, v247
	s_nop 1
	v_div_fmas_f32 v245, v245, v246, v248
	v_div_fixup_f32 v247, v245, v244, v77
	s_waitcnt vmcnt(7)
	v_lshlrev_b32_e32 v242, 16, v50
	v_and_b32_e32 v243, 0xffff0000, v50
	v_fmac_f32_e32 v242, v239, v2
	v_fmac_f32_e32 v243, v239, v3
	v_cvt_pk_bf16_f32 v82, v242, v243
	v_lshlrev_b32_e32 v242, 16, v51
	v_and_b32_e32 v243, 0xffff0000, v51
	v_fmac_f32_e32 v242, v239, v4
	v_fmac_f32_e32 v243, v239, v5
	v_cvt_pk_bf16_f32 v83, v242, v243
	s_waitcnt vmcnt(6)
	v_lshlrev_b32_e32 v242, 16, v52
	v_and_b32_e32 v243, 0xffff0000, v52
	v_fmac_f32_e32 v242, v239, v6
	v_fmac_f32_e32 v243, v239, v7
	v_cvt_pk_bf16_f32 v84, v242, v243
	v_lshlrev_b32_e32 v242, 16, v53
	v_and_b32_e32 v243, 0xffff0000, v53
	v_fmac_f32_e32 v242, v239, v8
	v_fmac_f32_e32 v243, v239, v9
	v_cvt_pk_bf16_f32 v85, v242, v243
	s_waitcnt vmcnt(5)
	v_lshlrev_b32_e32 v242, 16, v54
	v_and_b32_e32 v243, 0xffff0000, v54
	v_fmac_f32_e32 v242, v239, v10
	v_fmac_f32_e32 v243, v239, v11
	v_cvt_pk_bf16_f32 v86, v242, v243
	v_lshlrev_b32_e32 v242, 16, v55
	v_and_b32_e32 v243, 0xffff0000, v55
	v_fmac_f32_e32 v242, v239, v12
	v_fmac_f32_e32 v243, v239, v13
	v_cvt_pk_bf16_f32 v87, v242, v243
	s_waitcnt vmcnt(4)
	v_lshlrev_b32_e32 v242, 16, v56
	v_and_b32_e32 v243, 0xffff0000, v56
	v_fmac_f32_e32 v242, v239, v14
	v_fmac_f32_e32 v243, v239, v15
	v_cvt_pk_bf16_f32 v88, v242, v243
	v_lshlrev_b32_e32 v242, 16, v57
	v_and_b32_e32 v243, 0xffff0000, v57
	v_fmac_f32_e32 v242, v239, v16
	v_fmac_f32_e32 v243, v239, v17
	v_cvt_pk_bf16_f32 v89, v242, v243
	s_waitcnt vmcnt(3)
	v_lshlrev_b32_e32 v250, 16, v58
	v_and_b32_e32 v251, 0xffff0000, v58
	v_fmac_f32_e32 v250, v247, v18
	v_fmac_f32_e32 v251, v247, v19
	v_cvt_pk_bf16_f32 v90, v250, v251
	v_lshlrev_b32_e32 v250, 16, v59
	v_and_b32_e32 v251, 0xffff0000, v59
	v_fmac_f32_e32 v250, v247, v20
	v_fmac_f32_e32 v251, v247, v21
	v_cvt_pk_bf16_f32 v91, v250, v251
	s_waitcnt vmcnt(2)
	v_lshlrev_b32_e32 v250, 16, v60
	v_and_b32_e32 v251, 0xffff0000, v60
	v_fmac_f32_e32 v250, v247, v22
	v_fmac_f32_e32 v251, v247, v23
	v_cvt_pk_bf16_f32 v92, v250, v251
	v_lshlrev_b32_e32 v250, 16, v61
	v_and_b32_e32 v251, 0xffff0000, v61
	v_fmac_f32_e32 v250, v247, v24
	v_fmac_f32_e32 v251, v247, v25
	v_cvt_pk_bf16_f32 v93, v250, v251
	s_waitcnt vmcnt(1)
	v_lshlrev_b32_e32 v250, 16, v62
	v_and_b32_e32 v251, 0xffff0000, v62
	v_fmac_f32_e32 v250, v247, v26
	v_fmac_f32_e32 v251, v247, v27
	v_cvt_pk_bf16_f32 v94, v250, v251
	v_lshlrev_b32_e32 v250, 16, v63
	v_and_b32_e32 v251, 0xffff0000, v63
	v_fmac_f32_e32 v250, v247, v28
	v_fmac_f32_e32 v251, v247, v29
	v_cvt_pk_bf16_f32 v95, v250, v251
	s_waitcnt vmcnt(0)
	v_lshlrev_b32_e32 v250, 16, v64
	v_and_b32_e32 v251, 0xffff0000, v64
	v_fmac_f32_e32 v250, v247, v30
	v_fmac_f32_e32 v251, v247, v31
	v_cvt_pk_bf16_f32 v96, v250, v251
	v_lshlrev_b32_e32 v250, 16, v65
	v_and_b32_e32 v251, 0xffff0000, v65
	v_fmac_f32_e32 v250, v247, v32
	v_fmac_f32_e32 v251, v247, v33
	v_cvt_pk_bf16_f32 v97, v250, v251
	global_store_dwordx2 v72, v[82:83], s[14:15] offset:0
	global_store_dwordx2 v72, v[84:85], s[14:15] offset:32
	global_store_dwordx2 v72, v[86:87], s[14:15] offset:64
	global_store_dwordx2 v72, v[88:89], s[14:15] offset:96
	global_store_dwordx2 v73, v[90:91], s[14:15] offset:0
	global_store_dwordx2 v73, v[92:93], s[14:15] offset:32
	global_store_dwordx2 v73, v[94:95], s[14:15] offset:64
	global_store_dwordx2 v73, v[96:97], s[14:15] offset:96
	s_waitcnt vmcnt(0)
	s_add_i32 s54, s54, 1
	s_cmp_eq_u32 s54, 1
	s_cbranch_scc1 .Lnsa_mode_top
	v_cmp_gt_u32_e32 vcc, 0x44, v183
	s_nop 0
	s_and_saveexec_b64 s[20:21], vcc
	s_cbranch_execz .Lnsa_zskip_28
	v_lshlrev_b32_e32 v50, 2, v183
	v_add_u32_e32 v50, 0x1fc40, v50
	ds_write_b32 v50, v1
